# full stack with the GEMM compute-segment barrier 8 MFMAs early (prio-3 tail)
# baseline (speedup 1.0000x reference)
.LBB0_115:
	ds_read_b128 v[148:151], v154
	ds_read_b128 v[158:161], v154 offset:1024
	ds_read_b128 v[162:165], v154 offset:2048
	ds_read_b128 v[166:169], v154 offset:3072
	ds_read_b128 v[170:173], v155
	ds_read_b128 v[174:177], v155 offset:1024
	ds_read_b128 v[178:181], v155 offset:2048
	ds_read_b128 v[182:185], v155 offset:3072
	s_add_u32 s46, s44, 0xfff00080
	s_addc_u32 s47, s45, -1
	s_cmp_eq_u32 s69, 60
	s_cselect_b32 s49, s35, s47
	s_cselect_b32 s48, s43, s46
	s_cselect_b32 s47, s37, s68
	s_cselect_b32 s46, s66, s67
	v_lshl_add_u64 v[218:219], s[44:45], 0, v[140:141]
	s_add_i32 m0, s54, 0xc000
	ds_read_b128 v[186:189], v156
	ds_read_b128 v[190:193], v156 offset:1024
	ds_read_b128 v[194:197], v156 offset:2048
	ds_read_b128 v[198:201], v156 offset:3072
	ds_read_b128 v[202:205], v156 offset:4096
	ds_read_b128 v[206:209], v156 offset:5120
	ds_read_b128 v[210:213], v156 offset:6144
	ds_read_b128 v[214:217], v156 offset:7168
	global_load_lds_dwordx4 v[218:219], off
	v_lshl_add_u64 v[218:219], s[44:45], 0, v[142:143]
	s_add_i32 m0, s54, 0xe000
	s_nop 0
	global_load_lds_dwordx4 v[218:219], off
	s_waitcnt vmcnt(8)
	s_waitcnt lgkmcnt(0)
	s_barrier
	s_setprio 1
	s_waitcnt lgkmcnt(0)
	v_mfma_f32_16x16x32_bf16 v[126:129], v[148:151], v[186:189], v[126:129]
	v_mfma_f32_16x16x32_bf16 v[122:125], v[162:165], v[186:189], v[122:125]
	v_mfma_f32_16x16x32_bf16 v[118:121], v[148:151], v[194:197], v[118:121]
	v_mfma_f32_16x16x32_bf16 v[110:113], v[162:165], v[194:197], v[110:113]
	v_mfma_f32_16x16x32_bf16 v[102:105], v[148:151], v[202:205], v[102:105]
	v_mfma_f32_16x16x32_bf16 v[94:97], v[162:165], v[202:205], v[94:97]
	v_mfma_f32_16x16x32_bf16 v[86:89], v[148:151], v[210:213], v[86:89]
	v_mfma_f32_16x16x32_bf16 v[78:81], v[162:165], v[210:213], v[78:81]
	v_mfma_f32_16x16x32_bf16 v[126:129], v[158:161], v[190:193], v[126:129]
	v_mfma_f32_16x16x32_bf16 v[122:125], v[166:169], v[190:193], v[122:125]
	v_mfma_f32_16x16x32_bf16 v[118:121], v[158:161], v[198:201], v[118:121]
	v_mfma_f32_16x16x32_bf16 v[110:113], v[166:169], v[198:201], v[110:113]
	v_mfma_f32_16x16x32_bf16 v[102:105], v[158:161], v[206:209], v[102:105]
	v_mfma_f32_16x16x32_bf16 v[94:97], v[166:169], v[206:209], v[94:97]
	v_mfma_f32_16x16x32_bf16 v[86:89], v[158:161], v[214:217], v[86:89]
	v_mfma_f32_16x16x32_bf16 v[78:81], v[166:169], v[214:217], v[78:81]
	s_setprio 0
	s_setprio 1
	v_mfma_f32_16x16x32_bf16 v[114:117], v[170:173], v[186:189], v[114:117]
	v_mfma_f32_16x16x32_bf16 v[106:109], v[178:181], v[186:189], v[106:109]
	v_mfma_f32_16x16x32_bf16 v[98:101], v[170:173], v[194:197], v[98:101]
	v_mfma_f32_16x16x32_bf16 v[90:93], v[178:181], v[194:197], v[90:93]
	v_mfma_f32_16x16x32_bf16 v[82:85], v[170:173], v[202:205], v[82:85]
	v_mfma_f32_16x16x32_bf16 v[74:77], v[178:181], v[202:205], v[74:77]
	v_mfma_f32_16x16x32_bf16 v[70:73], v[170:173], v[210:213], v[70:73]
	v_mfma_f32_16x16x32_bf16 v[66:69], v[178:181], v[210:213], v[66:69]
	s_setprio 3
	s_barrier
	v_mfma_f32_16x16x32_bf16 v[114:117], v[174:177], v[190:193], v[114:117]
	v_mfma_f32_16x16x32_bf16 v[106:109], v[182:185], v[190:193], v[106:109]
	v_mfma_f32_16x16x32_bf16 v[98:101], v[174:177], v[198:201], v[98:101]
	v_mfma_f32_16x16x32_bf16 v[90:93], v[182:185], v[198:201], v[90:93]
	v_mfma_f32_16x16x32_bf16 v[82:85], v[174:177], v[206:209], v[82:85]
	v_mfma_f32_16x16x32_bf16 v[74:77], v[182:185], v[206:209], v[74:77]
	v_mfma_f32_16x16x32_bf16 v[70:73], v[174:177], v[214:217], v[70:73]
	v_mfma_f32_16x16x32_bf16 v[66:69], v[182:185], v[214:217], v[66:69]
	s_setprio 0
	s_add_i32 s70, s64, s51
	v_lshl_add_u64 v[218:219], s[46:47], 0, v[134:135]
	s_mov_b32 m0, s70
	ds_read_b128 v[186:189], v156 offset:16384
	ds_read_b128 v[190:193], v156 offset:17408
	ds_read_b128 v[194:197], v156 offset:18432
	ds_read_b128 v[198:201], v156 offset:19456
	ds_read_b128 v[202:205], v156 offset:20480
	ds_read_b128 v[206:209], v156 offset:21504
	ds_read_b128 v[210:213], v156 offset:22528
	ds_read_b128 v[214:217], v156 offset:23552
	global_load_lds_dwordx4 v[218:219], off
	s_add_i32 m0, s70, 0x2000
	s_add_u32 s70, s46, 0x100000
	v_lshl_add_u64 v[220:221], s[46:47], 0, v[130:131]
	s_addc_u32 s71, s47, 0
	s_add_i32 s72, s65, s51
	global_load_lds_dwordx4 v[220:221], off
	v_lshl_add_u64 v[222:223], s[70:71], 0, v[134:135]
	s_mov_b32 m0, s72
	v_lshl_add_u64 v[224:225], s[48:49], 0, v[132:133]
	global_load_lds_dwordx4 v[222:223], off
	v_lshl_add_u64 v[222:223], s[70:71], 0, v[130:131]
	s_add_i32 m0, s72, 0x2000
	s_nop 0
	global_load_lds_dwordx4 v[222:223], off
	v_lshl_add_u64 v[222:223], s[48:49], 0, v[136:137]
	s_mov_b32 m0, s54
	s_nop 0
	global_load_lds_dwordx4 v[222:223], off
	s_mov_b32 m0, s55
	s_nop 0
	global_load_lds_dwordx4 v[224:225], off
	s_waitcnt vmcnt(8)
	s_waitcnt lgkmcnt(0)
	s_barrier
	s_setprio 1
	s_waitcnt lgkmcnt(0)
	v_mfma_f32_16x16x32_bf16 v[62:65], v[148:151], v[186:189], v[62:65]
	v_mfma_f32_16x16x32_bf16 v[58:61], v[162:165], v[186:189], v[58:61]
	v_mfma_f32_16x16x32_bf16 v[54:57], v[148:151], v[194:197], v[54:57]
	v_mfma_f32_16x16x32_bf16 v[46:49], v[162:165], v[194:197], v[46:49]
	v_mfma_f32_16x16x32_bf16 v[38:41], v[148:151], v[202:205], v[38:41]
	v_mfma_f32_16x16x32_bf16 v[30:33], v[162:165], v[202:205], v[30:33]
	v_mfma_f32_16x16x32_bf16 v[22:25], v[148:151], v[210:213], v[22:25]
	v_mfma_f32_16x16x32_bf16 v[14:17], v[162:165], v[210:213], v[14:17]
	v_mfma_f32_16x16x32_bf16 v[62:65], v[158:161], v[190:193], v[62:65]
	v_mfma_f32_16x16x32_bf16 v[58:61], v[166:169], v[190:193], v[58:61]
	v_mfma_f32_16x16x32_bf16 v[54:57], v[158:161], v[198:201], v[54:57]
	v_mfma_f32_16x16x32_bf16 v[46:49], v[166:169], v[198:201], v[46:49]
	v_mfma_f32_16x16x32_bf16 v[38:41], v[158:161], v[206:209], v[38:41]
	v_mfma_f32_16x16x32_bf16 v[30:33], v[166:169], v[206:209], v[30:33]
	v_mfma_f32_16x16x32_bf16 v[22:25], v[158:161], v[214:217], v[22:25]
	v_mfma_f32_16x16x32_bf16 v[14:17], v[166:169], v[214:217], v[14:17]
	s_setprio 0
	s_setprio 1
	v_mfma_f32_16x16x32_bf16 v[50:53], v[170:173], v[186:189], v[50:53]
	v_mfma_f32_16x16x32_bf16 v[42:45], v[178:181], v[186:189], v[42:45]
	v_mfma_f32_16x16x32_bf16 v[34:37], v[170:173], v[194:197], v[34:37]
	v_mfma_f32_16x16x32_bf16 v[26:29], v[178:181], v[194:197], v[26:29]
	v_mfma_f32_16x16x32_bf16 v[18:21], v[170:173], v[202:205], v[18:21]
	v_mfma_f32_16x16x32_bf16 v[10:13], v[178:181], v[202:205], v[10:13]
	v_mfma_f32_16x16x32_bf16 v[6:9], v[170:173], v[210:213], v[6:9]
	v_mfma_f32_16x16x32_bf16 v[2:5], v[178:181], v[210:213], v[2:5]
	s_setprio 3
	s_barrier
	v_mfma_f32_16x16x32_bf16 v[50:53], v[174:177], v[190:193], v[50:53]
	v_mfma_f32_16x16x32_bf16 v[42:45], v[182:185], v[190:193], v[42:45]
	v_mfma_f32_16x16x32_bf16 v[34:37], v[174:177], v[198:201], v[34:37]
	v_mfma_f32_16x16x32_bf16 v[26:29], v[182:185], v[198:201], v[26:29]
	v_mfma_f32_16x16x32_bf16 v[18:21], v[174:177], v[206:209], v[18:21]
	v_mfma_f32_16x16x32_bf16 v[10:13], v[182:185], v[206:209], v[10:13]
	v_mfma_f32_16x16x32_bf16 v[6:9], v[174:177], v[214:217], v[6:9]
	v_mfma_f32_16x16x32_bf16 v[2:5], v[182:185], v[214:217], v[2:5]
	s_setprio 0
	s_add_i32 s70, 0, 0x18000
	v_add_u32_e32 v138, s70, v152
	s_add_i32 s71, 0, 0x1c000
	ds_read_b128 v[148:151], v138
	ds_read_b128 v[158:161], v138 offset:1024
	ds_read_b128 v[162:165], v138 offset:2048
	ds_read_b128 v[166:169], v138 offset:3072
	v_add_u32_e32 v138, s71, v152
	ds_read_b128 v[170:173], v138
	ds_read_b128 v[174:177], v138 offset:1024
	ds_read_b128 v[178:181], v138 offset:2048
	ds_read_b128 v[182:185], v138 offset:3072
	s_add_u32 s48, s48, 0x100000
	s_addc_u32 s49, s49, 0
	s_mov_b32 m0, s56
	v_lshl_add_u64 v[226:227], s[48:49], 0, v[136:137]
	ds_read_b128 v[186:189], v156 offset:32768
	ds_read_b128 v[190:193], v156 offset:33792
	ds_read_b128 v[194:197], v156 offset:34816
	ds_read_b128 v[198:201], v156 offset:35840
	ds_read_b128 v[202:205], v156 offset:36864
	ds_read_b128 v[206:209], v156 offset:37888
	ds_read_b128 v[210:213], v156 offset:38912
	ds_read_b128 v[214:217], v156 offset:39936
	global_load_lds_dwordx4 v[226:227], off
	v_lshl_add_u64 v[226:227], s[48:49], 0, v[132:133]
	s_mov_b32 m0, s57
	s_nop 0
	global_load_lds_dwordx4 v[226:227], off
	s_waitcnt vmcnt(8)
	s_waitcnt lgkmcnt(0)
	s_barrier
	s_setprio 1
	s_waitcnt lgkmcnt(0)
	v_mfma_f32_16x16x32_bf16 v[126:129], v[148:151], v[186:189], v[126:129]
	v_mfma_f32_16x16x32_bf16 v[122:125], v[162:165], v[186:189], v[122:125]
	v_mfma_f32_16x16x32_bf16 v[118:121], v[148:151], v[194:197], v[118:121]
	v_mfma_f32_16x16x32_bf16 v[110:113], v[162:165], v[194:197], v[110:113]
	v_mfma_f32_16x16x32_bf16 v[102:105], v[148:151], v[202:205], v[102:105]
	v_mfma_f32_16x16x32_bf16 v[94:97], v[162:165], v[202:205], v[94:97]
	v_mfma_f32_16x16x32_bf16 v[86:89], v[148:151], v[210:213], v[86:89]
	v_mfma_f32_16x16x32_bf16 v[78:81], v[162:165], v[210:213], v[78:81]
	v_mfma_f32_16x16x32_bf16 v[126:129], v[158:161], v[190:193], v[126:129]
	v_mfma_f32_16x16x32_bf16 v[122:125], v[166:169], v[190:193], v[122:125]
	v_mfma_f32_16x16x32_bf16 v[118:121], v[158:161], v[198:201], v[118:121]
	v_mfma_f32_16x16x32_bf16 v[110:113], v[166:169], v[198:201], v[110:113]
	v_mfma_f32_16x16x32_bf16 v[102:105], v[158:161], v[206:209], v[102:105]
	v_mfma_f32_16x16x32_bf16 v[94:97], v[166:169], v[206:209], v[94:97]
	v_mfma_f32_16x16x32_bf16 v[86:89], v[158:161], v[214:217], v[86:89]
	v_mfma_f32_16x16x32_bf16 v[78:81], v[166:169], v[214:217], v[78:81]
	s_setprio 0
	s_setprio 1
	v_mfma_f32_16x16x32_bf16 v[114:117], v[170:173], v[186:189], v[114:117]
	v_mfma_f32_16x16x32_bf16 v[106:109], v[178:181], v[186:189], v[106:109]
	v_mfma_f32_16x16x32_bf16 v[98:101], v[170:173], v[194:197], v[98:101]
	v_mfma_f32_16x16x32_bf16 v[90:93], v[178:181], v[194:197], v[90:93]
	v_mfma_f32_16x16x32_bf16 v[82:85], v[170:173], v[202:205], v[82:85]
	v_mfma_f32_16x16x32_bf16 v[74:77], v[178:181], v[202:205], v[74:77]
	v_mfma_f32_16x16x32_bf16 v[70:73], v[170:173], v[210:213], v[70:73]
	v_mfma_f32_16x16x32_bf16 v[66:69], v[178:181], v[210:213], v[66:69]
	s_setprio 3
	s_barrier
	v_mfma_f32_16x16x32_bf16 v[114:117], v[174:177], v[190:193], v[114:117]
	v_mfma_f32_16x16x32_bf16 v[106:109], v[182:185], v[190:193], v[106:109]
	v_mfma_f32_16x16x32_bf16 v[98:101], v[174:177], v[198:201], v[98:101]
	v_mfma_f32_16x16x32_bf16 v[90:93], v[182:185], v[198:201], v[90:93]
	v_mfma_f32_16x16x32_bf16 v[82:85], v[174:177], v[206:209], v[82:85]
	v_mfma_f32_16x16x32_bf16 v[74:77], v[182:185], v[206:209], v[74:77]
	v_mfma_f32_16x16x32_bf16 v[70:73], v[174:177], v[214:217], v[70:73]
	v_mfma_f32_16x16x32_bf16 v[66:69], v[182:185], v[214:217], v[66:69]
	s_setprio 0
	s_add_i32 s48, s70, s51
	v_lshl_add_u64 v[218:219], v[218:219], 0, s[28:29]
	s_mov_b32 m0, s48
	ds_read_b128 v[186:189], v156 offset:49152
	ds_read_b128 v[190:193], v156 offset:50176
	ds_read_b128 v[194:197], v156 offset:51200
	ds_read_b128 v[198:201], v156 offset:52224
	ds_read_b128 v[202:205], v156 offset:53248
	ds_read_b128 v[206:209], v156 offset:54272
	ds_read_b128 v[210:213], v156 offset:55296
	ds_read_b128 v[214:217], v156 offset:56320
	global_load_lds_dwordx4 v[218:219], off
	s_add_i32 m0, s48, 0x2000
	s_add_u32 s46, s46, 0x100080
	v_lshl_add_u64 v[218:219], v[220:221], 0, s[28:29]
	s_addc_u32 s47, s47, 0
	s_add_i32 s48, s71, s51
	global_load_lds_dwordx4 v[218:219], off
	v_lshl_add_u64 v[218:219], s[46:47], 0, v[134:135]
	s_mov_b32 m0, s48
	s_nop 0
	global_load_lds_dwordx4 v[218:219], off
	v_lshl_add_u64 v[218:219], s[46:47], 0, v[130:131]
	s_add_i32 m0, s48, 0x2000
	s_nop 0
	global_load_lds_dwordx4 v[218:219], off
	v_lshl_add_u64 v[218:219], v[222:223], 0, s[28:29]
	s_mov_b32 m0, s59
	s_nop 0
	global_load_lds_dwordx4 v[218:219], off
	v_lshl_add_u64 v[218:219], v[224:225], 0, s[28:29]
	s_mov_b32 m0, s60
	s_nop 0
	global_load_lds_dwordx4 v[218:219], off
	s_waitcnt vmcnt(8)
	s_waitcnt lgkmcnt(0)
	s_barrier
	s_setprio 1
	s_waitcnt lgkmcnt(0)
	v_mfma_f32_16x16x32_bf16 v[62:65], v[148:151], v[186:189], v[62:65]
	v_mfma_f32_16x16x32_bf16 v[58:61], v[162:165], v[186:189], v[58:61]
	v_mfma_f32_16x16x32_bf16 v[54:57], v[148:151], v[194:197], v[54:57]
	v_mfma_f32_16x16x32_bf16 v[46:49], v[162:165], v[194:197], v[46:49]
	v_mfma_f32_16x16x32_bf16 v[38:41], v[148:151], v[202:205], v[38:41]
	v_mfma_f32_16x16x32_bf16 v[30:33], v[162:165], v[202:205], v[30:33]
	v_mfma_f32_16x16x32_bf16 v[22:25], v[148:151], v[210:213], v[22:25]
	v_mfma_f32_16x16x32_bf16 v[14:17], v[162:165], v[210:213], v[14:17]
	v_mfma_f32_16x16x32_bf16 v[62:65], v[158:161], v[190:193], v[62:65]
	v_mfma_f32_16x16x32_bf16 v[58:61], v[166:169], v[190:193], v[58:61]
	v_mfma_f32_16x16x32_bf16 v[54:57], v[158:161], v[198:201], v[54:57]
	v_mfma_f32_16x16x32_bf16 v[46:49], v[166:169], v[198:201], v[46:49]
	v_mfma_f32_16x16x32_bf16 v[38:41], v[158:161], v[206:209], v[38:41]
	v_mfma_f32_16x16x32_bf16 v[30:33], v[166:169], v[206:209], v[30:33]
	v_mfma_f32_16x16x32_bf16 v[22:25], v[158:161], v[214:217], v[22:25]
	v_mfma_f32_16x16x32_bf16 v[14:17], v[166:169], v[214:217], v[14:17]
	s_setprio 0
	s_setprio 1
	v_mfma_f32_16x16x32_bf16 v[50:53], v[170:173], v[186:189], v[50:53]
	v_mfma_f32_16x16x32_bf16 v[42:45], v[178:181], v[186:189], v[42:45]
	v_mfma_f32_16x16x32_bf16 v[34:37], v[170:173], v[194:197], v[34:37]
	v_mfma_f32_16x16x32_bf16 v[26:29], v[178:181], v[194:197], v[26:29]
	v_mfma_f32_16x16x32_bf16 v[18:21], v[170:173], v[202:205], v[18:21]
	v_mfma_f32_16x16x32_bf16 v[10:13], v[178:181], v[202:205], v[10:13]
	v_mfma_f32_16x16x32_bf16 v[6:9], v[170:173], v[210:213], v[6:9]
	v_mfma_f32_16x16x32_bf16 v[2:5], v[178:181], v[210:213], v[2:5]
	s_setprio 3
	s_barrier
	v_mfma_f32_16x16x32_bf16 v[50:53], v[174:177], v[190:193], v[50:53]
	v_mfma_f32_16x16x32_bf16 v[42:45], v[182:185], v[190:193], v[42:45]
	v_mfma_f32_16x16x32_bf16 v[34:37], v[174:177], v[198:201], v[34:37]
	v_mfma_f32_16x16x32_bf16 v[26:29], v[182:185], v[198:201], v[26:29]
	v_mfma_f32_16x16x32_bf16 v[18:21], v[174:177], v[206:209], v[18:21]
	v_mfma_f32_16x16x32_bf16 v[10:13], v[182:185], v[206:209], v[10:13]
	v_mfma_f32_16x16x32_bf16 v[6:9], v[174:177], v[214:217], v[6:9]
	v_mfma_f32_16x16x32_bf16 v[2:5], v[182:185], v[214:217], v[2:5]
	s_setprio 0
	s_add_i32 s69, s69, 2
	s_add_u32 s44, s44, 0x100
	s_addc_u32 s45, s45, 0
	s_add_u32 s67, s67, 0x100
	s_addc_u32 s68, s68, 0
	s_cmp_gt_u32 s69, 61
	s_cbranch_scc0 .LBB0_115
	s_and_b64 vcc, exec, s[30:31]
	s_cbranch_vccz .LBB0_118
	s_barrier

.LBB0_540:
	v_add_u32_e32 v139, s64, v186
	ds_read_b128 v[130:133], v139
	ds_read_b128 v[134:137], v139 offset:1024
	ds_read_b128 v[146:149], v139 offset:2048
	ds_read_b128 v[150:153], v139 offset:3072
	v_add_u32_e32 v139, s65, v186
	s_add_u32 s48, s44, s46
	ds_read_b128 v[154:157], v139
	ds_read_b128 v[174:177], v139 offset:1024
	ds_read_b128 v[178:181], v139 offset:2048
	ds_read_b128 v[182:185], v139 offset:3072
	s_addc_u32 s49, s45, s47
	s_add_u32 s48, s48, 0x100
	s_addc_u32 s49, s49, 0
	s_add_u32 s71, s68, s46
	s_addc_u32 s72, s69, s47
	s_cmpk_eq_i32 s46, 0x1f00
	s_cselect_b32 s51, s39, s49
	s_cselect_b32 s50, s66, s48
	s_cselect_b32 s49, s37, s72
	s_cselect_b32 s48, s67, s71
	v_lshl_add_u64 v[222:223], v[142:143], 0, s[46:47]
	s_add_i32 m0, s55, 0xc000
	ds_read_b128 v[190:193], v188
	ds_read_b128 v[194:197], v188 offset:1024
	ds_read_b128 v[198:201], v188 offset:2048
	ds_read_b128 v[202:205], v188 offset:3072
	ds_read_b128 v[206:209], v188 offset:4096
	ds_read_b128 v[210:213], v188 offset:5120
	ds_read_b128 v[214:217], v188 offset:6144
	ds_read_b128 v[218:221], v188 offset:7168
	global_load_lds_dwordx4 v[222:223], off
	v_lshl_add_u64 v[222:223], v[144:145], 0, s[46:47]
	s_add_i32 m0, s55, 0xe000
	s_nop 0
	global_load_lds_dwordx4 v[222:223], off
	s_waitcnt vmcnt(8)
	s_waitcnt lgkmcnt(0)
	s_barrier
	s_setprio 1
	s_waitcnt lgkmcnt(0)
	v_mfma_f32_16x16x32_bf16 v[126:129], v[130:133], v[190:193], v[126:129]
	v_mfma_f32_16x16x32_bf16 v[122:125], v[146:149], v[190:193], v[122:125]
	v_mfma_f32_16x16x32_bf16 v[114:117], v[130:133], v[198:201], v[114:117]
	v_mfma_f32_16x16x32_bf16 v[106:109], v[146:149], v[198:201], v[106:109]
	v_mfma_f32_16x16x32_bf16 v[98:101], v[130:133], v[206:209], v[98:101]
	v_mfma_f32_16x16x32_bf16 v[90:93], v[146:149], v[206:209], v[90:93]
	v_mfma_f32_16x16x32_bf16 v[82:85], v[130:133], v[214:217], v[82:85]
	v_mfma_f32_16x16x32_bf16 v[74:77], v[146:149], v[214:217], v[74:77]
	v_mfma_f32_16x16x32_bf16 v[126:129], v[134:137], v[194:197], v[126:129]
	v_mfma_f32_16x16x32_bf16 v[122:125], v[150:153], v[194:197], v[122:125]
	v_mfma_f32_16x16x32_bf16 v[114:117], v[134:137], v[202:205], v[114:117]
	v_mfma_f32_16x16x32_bf16 v[106:109], v[150:153], v[202:205], v[106:109]
	v_mfma_f32_16x16x32_bf16 v[98:101], v[134:137], v[210:213], v[98:101]
	v_mfma_f32_16x16x32_bf16 v[90:93], v[150:153], v[210:213], v[90:93]
	v_mfma_f32_16x16x32_bf16 v[82:85], v[134:137], v[218:221], v[82:85]
	v_mfma_f32_16x16x32_bf16 v[74:77], v[150:153], v[218:221], v[74:77]
	s_setprio 0
	s_setprio 1
	v_mfma_f32_16x16x32_bf16 v[118:121], v[154:157], v[190:193], v[118:121]
	v_mfma_f32_16x16x32_bf16 v[110:113], v[178:181], v[190:193], v[110:113]
	v_mfma_f32_16x16x32_bf16 v[102:105], v[154:157], v[198:201], v[102:105]
	v_mfma_f32_16x16x32_bf16 v[94:97], v[178:181], v[198:201], v[94:97]
	v_mfma_f32_16x16x32_bf16 v[86:89], v[154:157], v[206:209], v[86:89]
	v_mfma_f32_16x16x32_bf16 v[78:81], v[178:181], v[206:209], v[78:81]
	v_mfma_f32_16x16x32_bf16 v[70:73], v[154:157], v[214:217], v[70:73]
	v_mfma_f32_16x16x32_bf16 v[66:69], v[178:181], v[214:217], v[66:69]
	s_setprio 3
	s_barrier
	v_mfma_f32_16x16x32_bf16 v[118:121], v[174:177], v[194:197], v[118:121]
	v_mfma_f32_16x16x32_bf16 v[110:113], v[182:185], v[194:197], v[110:113]
	v_mfma_f32_16x16x32_bf16 v[102:105], v[174:177], v[202:205], v[102:105]
	v_mfma_f32_16x16x32_bf16 v[94:97], v[182:185], v[202:205], v[94:97]
	v_mfma_f32_16x16x32_bf16 v[86:89], v[174:177], v[210:213], v[86:89]
	v_mfma_f32_16x16x32_bf16 v[78:81], v[182:185], v[210:213], v[78:81]
	v_mfma_f32_16x16x32_bf16 v[70:73], v[174:177], v[218:221], v[70:73]
	v_mfma_f32_16x16x32_bf16 v[66:69], v[182:185], v[218:221], v[66:69]
	s_setprio 0
	s_add_i32 s71, s64, s54
	v_lshl_add_u64 v[222:223], s[48:49], 0, v[160:161]
	s_mov_b32 m0, s71
	ds_read_b128 v[190:193], v188 offset:16384
	ds_read_b128 v[194:197], v188 offset:17408
	ds_read_b128 v[198:201], v188 offset:18432
	ds_read_b128 v[202:205], v188 offset:19456
	ds_read_b128 v[206:209], v188 offset:20480
	ds_read_b128 v[210:213], v188 offset:21504
	ds_read_b128 v[214:217], v188 offset:22528
	ds_read_b128 v[218:221], v188 offset:23552
	global_load_lds_dwordx4 v[222:223], off
	s_add_i32 m0, s71, 0x2000
	s_add_u32 s72, s48, 0x100000
	v_lshl_add_u64 v[224:225], s[48:49], 0, v[164:165]
	s_addc_u32 s73, s49, 0
	s_add_i32 s71, s65, s54
	global_load_lds_dwordx4 v[224:225], off
	v_lshl_add_u64 v[226:227], s[72:73], 0, v[160:161]
	s_mov_b32 m0, s71
	v_lshl_add_u64 v[228:229], s[50:51], 0, v[162:163]
	global_load_lds_dwordx4 v[226:227], off
	v_lshl_add_u64 v[226:227], s[72:73], 0, v[164:165]
	s_add_i32 m0, s71, 0x2000
	s_nop 0
	global_load_lds_dwordx4 v[226:227], off
	v_lshl_add_u64 v[226:227], s[50:51], 0, v[158:159]
	s_mov_b32 m0, s55
	s_nop 0
	global_load_lds_dwordx4 v[226:227], off
	s_mov_b32 m0, s56
	s_nop 0
	global_load_lds_dwordx4 v[228:229], off
	s_waitcnt vmcnt(8)
	s_waitcnt lgkmcnt(0)
	s_barrier
	s_setprio 1
	s_waitcnt lgkmcnt(0)
	v_mfma_f32_16x16x32_bf16 v[62:65], v[130:133], v[190:193], v[62:65]
	v_mfma_f32_16x16x32_bf16 v[58:61], v[146:149], v[190:193], v[58:61]
	v_mfma_f32_16x16x32_bf16 v[50:53], v[130:133], v[198:201], v[50:53]
	v_mfma_f32_16x16x32_bf16 v[42:45], v[146:149], v[198:201], v[42:45]
	v_mfma_f32_16x16x32_bf16 v[34:37], v[130:133], v[206:209], v[34:37]
	v_mfma_f32_16x16x32_bf16 v[26:29], v[146:149], v[206:209], v[26:29]
	v_mfma_f32_16x16x32_bf16 v[18:21], v[130:133], v[214:217], v[18:21]
	v_mfma_f32_16x16x32_bf16 v[10:13], v[146:149], v[214:217], v[10:13]
	v_mfma_f32_16x16x32_bf16 v[62:65], v[134:137], v[194:197], v[62:65]
	v_mfma_f32_16x16x32_bf16 v[58:61], v[150:153], v[194:197], v[58:61]
	v_mfma_f32_16x16x32_bf16 v[50:53], v[134:137], v[202:205], v[50:53]
	v_mfma_f32_16x16x32_bf16 v[42:45], v[150:153], v[202:205], v[42:45]
	v_mfma_f32_16x16x32_bf16 v[34:37], v[134:137], v[210:213], v[34:37]
	v_mfma_f32_16x16x32_bf16 v[26:29], v[150:153], v[210:213], v[26:29]
	v_mfma_f32_16x16x32_bf16 v[18:21], v[134:137], v[218:221], v[18:21]
	v_mfma_f32_16x16x32_bf16 v[10:13], v[150:153], v[218:221], v[10:13]
	s_setprio 0
	s_setprio 1
	v_mfma_f32_16x16x32_bf16 v[54:57], v[154:157], v[190:193], v[54:57]
	v_mfma_f32_16x16x32_bf16 v[46:49], v[178:181], v[190:193], v[46:49]
	v_mfma_f32_16x16x32_bf16 v[38:41], v[154:157], v[198:201], v[38:41]
	v_mfma_f32_16x16x32_bf16 v[30:33], v[178:181], v[198:201], v[30:33]
	v_mfma_f32_16x16x32_bf16 v[22:25], v[154:157], v[206:209], v[22:25]
	v_mfma_f32_16x16x32_bf16 v[14:17], v[178:181], v[206:209], v[14:17]
	v_mfma_f32_16x16x32_bf16 v[6:9], v[154:157], v[214:217], v[6:9]
	v_mfma_f32_16x16x32_bf16 v[2:5], v[178:181], v[214:217], v[2:5]
	s_setprio 3
	s_barrier
	v_mfma_f32_16x16x32_bf16 v[54:57], v[174:177], v[194:197], v[54:57]
	v_mfma_f32_16x16x32_bf16 v[46:49], v[182:185], v[194:197], v[46:49]
	v_mfma_f32_16x16x32_bf16 v[38:41], v[174:177], v[202:205], v[38:41]
	v_mfma_f32_16x16x32_bf16 v[30:33], v[182:185], v[202:205], v[30:33]
	v_mfma_f32_16x16x32_bf16 v[22:25], v[174:177], v[210:213], v[22:25]
	v_mfma_f32_16x16x32_bf16 v[14:17], v[182:185], v[210:213], v[14:17]
	v_mfma_f32_16x16x32_bf16 v[6:9], v[174:177], v[218:221], v[6:9]
	v_mfma_f32_16x16x32_bf16 v[2:5], v[182:185], v[218:221], v[2:5]
	s_setprio 0
	s_add_i32 s71, 0, 0x18000
	v_add_u32_e32 v139, s71, v186
	s_add_i32 s72, 0, 0x1c000
	ds_read_b128 v[130:133], v139
	ds_read_b128 v[134:137], v139 offset:1024
	ds_read_b128 v[146:149], v139 offset:2048
	ds_read_b128 v[150:153], v139 offset:3072
	v_add_u32_e32 v139, s72, v186
	ds_read_b128 v[154:157], v139
	ds_read_b128 v[174:177], v139 offset:1024
	ds_read_b128 v[178:181], v139 offset:2048
	ds_read_b128 v[182:185], v139 offset:3072
	s_add_u32 s50, s50, 0x100000
	s_addc_u32 s51, s51, 0
	s_mov_b32 m0, s57
	v_lshl_add_u64 v[230:231], s[50:51], 0, v[158:159]
	ds_read_b128 v[190:193], v188 offset:32768
	ds_read_b128 v[194:197], v188 offset:33792
	ds_read_b128 v[198:201], v188 offset:34816
	ds_read_b128 v[202:205], v188 offset:35840
	ds_read_b128 v[206:209], v188 offset:36864
	ds_read_b128 v[210:213], v188 offset:37888
	ds_read_b128 v[214:217], v188 offset:38912
	ds_read_b128 v[218:221], v188 offset:39936
	global_load_lds_dwordx4 v[230:231], off
	v_lshl_add_u64 v[230:231], s[50:51], 0, v[162:163]
	s_mov_b32 m0, s58
	s_nop 0
	global_load_lds_dwordx4 v[230:231], off
	s_waitcnt vmcnt(8)
	s_waitcnt lgkmcnt(0)
	s_barrier
	s_setprio 1
	s_waitcnt lgkmcnt(0)
	v_mfma_f32_16x16x32_bf16 v[126:129], v[130:133], v[190:193], v[126:129]
	v_mfma_f32_16x16x32_bf16 v[122:125], v[146:149], v[190:193], v[122:125]
	v_mfma_f32_16x16x32_bf16 v[114:117], v[130:133], v[198:201], v[114:117]
	v_mfma_f32_16x16x32_bf16 v[106:109], v[146:149], v[198:201], v[106:109]
	v_mfma_f32_16x16x32_bf16 v[98:101], v[130:133], v[206:209], v[98:101]
	v_mfma_f32_16x16x32_bf16 v[90:93], v[146:149], v[206:209], v[90:93]
	v_mfma_f32_16x16x32_bf16 v[82:85], v[130:133], v[214:217], v[82:85]
	v_mfma_f32_16x16x32_bf16 v[74:77], v[146:149], v[214:217], v[74:77]
	v_mfma_f32_16x16x32_bf16 v[126:129], v[134:137], v[194:197], v[126:129]
	v_mfma_f32_16x16x32_bf16 v[122:125], v[150:153], v[194:197], v[122:125]
	v_mfma_f32_16x16x32_bf16 v[114:117], v[134:137], v[202:205], v[114:117]
	v_mfma_f32_16x16x32_bf16 v[106:109], v[150:153], v[202:205], v[106:109]
	v_mfma_f32_16x16x32_bf16 v[98:101], v[134:137], v[210:213], v[98:101]
	v_mfma_f32_16x16x32_bf16 v[90:93], v[150:153], v[210:213], v[90:93]
	v_mfma_f32_16x16x32_bf16 v[82:85], v[134:137], v[218:221], v[82:85]
	v_mfma_f32_16x16x32_bf16 v[74:77], v[150:153], v[218:221], v[74:77]
	s_setprio 0
	s_setprio 1
	v_mfma_f32_16x16x32_bf16 v[118:121], v[154:157], v[190:193], v[118:121]
	v_mfma_f32_16x16x32_bf16 v[110:113], v[178:181], v[190:193], v[110:113]
	v_mfma_f32_16x16x32_bf16 v[102:105], v[154:157], v[198:201], v[102:105]
	v_mfma_f32_16x16x32_bf16 v[94:97], v[178:181], v[198:201], v[94:97]
	v_mfma_f32_16x16x32_bf16 v[86:89], v[154:157], v[206:209], v[86:89]
	v_mfma_f32_16x16x32_bf16 v[78:81], v[178:181], v[206:209], v[78:81]
	v_mfma_f32_16x16x32_bf16 v[70:73], v[154:157], v[214:217], v[70:73]
	v_mfma_f32_16x16x32_bf16 v[66:69], v[178:181], v[214:217], v[66:69]
	s_setprio 3
	s_barrier
	v_mfma_f32_16x16x32_bf16 v[118:121], v[174:177], v[194:197], v[118:121]
	v_mfma_f32_16x16x32_bf16 v[110:113], v[182:185], v[194:197], v[110:113]
	v_mfma_f32_16x16x32_bf16 v[102:105], v[174:177], v[202:205], v[102:105]
	v_mfma_f32_16x16x32_bf16 v[94:97], v[182:185], v[202:205], v[94:97]
	v_mfma_f32_16x16x32_bf16 v[86:89], v[174:177], v[210:213], v[86:89]
	v_mfma_f32_16x16x32_bf16 v[78:81], v[182:185], v[210:213], v[78:81]
	v_mfma_f32_16x16x32_bf16 v[70:73], v[174:177], v[218:221], v[70:73]
	v_mfma_f32_16x16x32_bf16 v[66:69], v[182:185], v[218:221], v[66:69]
	s_setprio 0
	s_add_i32 s50, s71, s54
	v_lshl_add_u64 v[222:223], v[222:223], 0, s[30:31]
	s_mov_b32 m0, s50
	ds_read_b128 v[190:193], v188 offset:49152
	ds_read_b128 v[194:197], v188 offset:50176
	ds_read_b128 v[198:201], v188 offset:51200
	ds_read_b128 v[202:205], v188 offset:52224
	ds_read_b128 v[206:209], v188 offset:53248
	ds_read_b128 v[210:213], v188 offset:54272
	ds_read_b128 v[214:217], v188 offset:55296
	ds_read_b128 v[218:221], v188 offset:56320
	global_load_lds_dwordx4 v[222:223], off
	s_add_i32 m0, s50, 0x2000
	s_add_u32 s48, s48, 0x100080
	v_lshl_add_u64 v[222:223], v[224:225], 0, s[30:31]
	s_addc_u32 s49, s49, 0
	s_add_i32 s50, s72, s54
	global_load_lds_dwordx4 v[222:223], off
	v_lshl_add_u64 v[222:223], s[48:49], 0, v[160:161]
	s_mov_b32 m0, s50
	s_nop 0
	global_load_lds_dwordx4 v[222:223], off
	v_lshl_add_u64 v[222:223], s[48:49], 0, v[164:165]
	s_add_i32 m0, s50, 0x2000
	s_nop 0
	global_load_lds_dwordx4 v[222:223], off
	v_lshl_add_u64 v[222:223], v[226:227], 0, s[30:31]
	s_mov_b32 m0, s60
	s_nop 0
	global_load_lds_dwordx4 v[222:223], off
	v_lshl_add_u64 v[222:223], v[228:229], 0, s[30:31]
	s_mov_b32 m0, s61
	s_nop 0
	global_load_lds_dwordx4 v[222:223], off
	s_waitcnt vmcnt(8)
	s_waitcnt lgkmcnt(0)
	s_barrier
	s_setprio 1
	s_waitcnt lgkmcnt(0)
	v_mfma_f32_16x16x32_bf16 v[62:65], v[130:133], v[190:193], v[62:65]
	v_mfma_f32_16x16x32_bf16 v[58:61], v[146:149], v[190:193], v[58:61]
	v_mfma_f32_16x16x32_bf16 v[50:53], v[130:133], v[198:201], v[50:53]
	v_mfma_f32_16x16x32_bf16 v[42:45], v[146:149], v[198:201], v[42:45]
	v_mfma_f32_16x16x32_bf16 v[34:37], v[130:133], v[206:209], v[34:37]
	v_mfma_f32_16x16x32_bf16 v[26:29], v[146:149], v[206:209], v[26:29]
	v_mfma_f32_16x16x32_bf16 v[18:21], v[130:133], v[214:217], v[18:21]
	v_mfma_f32_16x16x32_bf16 v[10:13], v[146:149], v[214:217], v[10:13]
	v_mfma_f32_16x16x32_bf16 v[62:65], v[134:137], v[194:197], v[62:65]
	v_mfma_f32_16x16x32_bf16 v[58:61], v[150:153], v[194:197], v[58:61]
	v_mfma_f32_16x16x32_bf16 v[50:53], v[134:137], v[202:205], v[50:53]
	v_mfma_f32_16x16x32_bf16 v[42:45], v[150:153], v[202:205], v[42:45]
	v_mfma_f32_16x16x32_bf16 v[34:37], v[134:137], v[210:213], v[34:37]
	v_mfma_f32_16x16x32_bf16 v[26:29], v[150:153], v[210:213], v[26:29]
	v_mfma_f32_16x16x32_bf16 v[18:21], v[134:137], v[218:221], v[18:21]
	v_mfma_f32_16x16x32_bf16 v[10:13], v[150:153], v[218:221], v[10:13]
	s_setprio 0
	s_setprio 1
	v_mfma_f32_16x16x32_bf16 v[54:57], v[154:157], v[190:193], v[54:57]
	v_mfma_f32_16x16x32_bf16 v[46:49], v[178:181], v[190:193], v[46:49]
	v_mfma_f32_16x16x32_bf16 v[38:41], v[154:157], v[198:201], v[38:41]
	v_mfma_f32_16x16x32_bf16 v[30:33], v[178:181], v[198:201], v[30:33]
	v_mfma_f32_16x16x32_bf16 v[22:25], v[154:157], v[206:209], v[22:25]
	v_mfma_f32_16x16x32_bf16 v[14:17], v[178:181], v[206:209], v[14:17]
	v_mfma_f32_16x16x32_bf16 v[6:9], v[154:157], v[214:217], v[6:9]
	v_mfma_f32_16x16x32_bf16 v[2:5], v[178:181], v[214:217], v[2:5]
	s_setprio 3
	s_barrier
	v_mfma_f32_16x16x32_bf16 v[54:57], v[174:177], v[194:197], v[54:57]
	v_mfma_f32_16x16x32_bf16 v[46:49], v[182:185], v[194:197], v[46:49]
	v_mfma_f32_16x16x32_bf16 v[38:41], v[174:177], v[202:205], v[38:41]
	v_mfma_f32_16x16x32_bf16 v[30:33], v[182:185], v[202:205], v[30:33]
	v_mfma_f32_16x16x32_bf16 v[22:25], v[174:177], v[210:213], v[22:25]
	v_mfma_f32_16x16x32_bf16 v[14:17], v[182:185], v[210:213], v[14:17]
	v_mfma_f32_16x16x32_bf16 v[6:9], v[174:177], v[218:221], v[6:9]
	v_mfma_f32_16x16x32_bf16 v[2:5], v[182:185], v[218:221], v[2:5]
	s_setprio 0
	s_add_i32 s70, s70, 2
	s_add_u32 s46, s46, 0x100
	s_addc_u32 s47, s47, 0
	s_cmp_gt_u32 s70, 61
	s_cbranch_scc1 .LBB0_543

.LBB0_618:
	ds_read_b128 v[146:149], v154
	ds_read_b128 v[158:161], v154 offset:1024
	ds_read_b128 v[162:165], v154 offset:2048
	ds_read_b128 v[166:169], v154 offset:3072
	ds_read_b128 v[170:173], v155
	ds_read_b128 v[174:177], v155 offset:1024
	ds_read_b128 v[178:181], v155 offset:2048
	ds_read_b128 v[182:185], v155 offset:3072
	s_add_u32 s48, s46, 0xfff00080
	s_addc_u32 s49, s47, -1
	s_cmp_eq_u32 s68, 60
	s_cselect_b32 s51, s39, s49
	s_cselect_b32 s50, s64, s48
	s_cselect_b32 s49, s37, s67
	s_cselect_b32 s48, s65, s66
	v_lshl_add_u64 v[150:151], s[46:47], 0, v[138:139]
	s_add_i32 m0, s45, 0xc000
	ds_read_b128 v[186:189], v156
	ds_read_b128 v[190:193], v156 offset:1024
	ds_read_b128 v[194:197], v156 offset:2048
	ds_read_b128 v[198:201], v156 offset:3072
	ds_read_b128 v[202:205], v156 offset:4096
	ds_read_b128 v[206:209], v156 offset:5120
	ds_read_b128 v[210:213], v156 offset:6144
	ds_read_b128 v[214:217], v156 offset:7168
	global_load_lds_dwordx4 v[150:151], off
	v_lshl_add_u64 v[150:151], s[46:47], 0, v[140:141]
	s_add_i32 m0, s45, 0xe000
	s_nop 0
	global_load_lds_dwordx4 v[150:151], off
	s_waitcnt vmcnt(8)
	s_waitcnt lgkmcnt(0)
	s_barrier
	s_setprio 1
	s_waitcnt lgkmcnt(0)
	v_mfma_f32_16x16x32_bf16 v[126:129], v[146:149], v[186:189], v[126:129]
	v_mfma_f32_16x16x32_bf16 v[122:125], v[162:165], v[186:189], v[122:125]
	v_mfma_f32_16x16x32_bf16 v[118:121], v[146:149], v[194:197], v[118:121]
	v_mfma_f32_16x16x32_bf16 v[114:117], v[162:165], v[194:197], v[114:117]
	v_mfma_f32_16x16x32_bf16 v[102:105], v[146:149], v[202:205], v[102:105]
	v_mfma_f32_16x16x32_bf16 v[98:101], v[162:165], v[202:205], v[98:101]
	v_mfma_f32_16x16x32_bf16 v[86:89], v[146:149], v[210:213], v[86:89]
	v_mfma_f32_16x16x32_bf16 v[78:81], v[162:165], v[210:213], v[78:81]
	v_mfma_f32_16x16x32_bf16 v[126:129], v[158:161], v[190:193], v[126:129]
	v_mfma_f32_16x16x32_bf16 v[122:125], v[166:169], v[190:193], v[122:125]
	v_mfma_f32_16x16x32_bf16 v[118:121], v[158:161], v[198:201], v[118:121]
	v_mfma_f32_16x16x32_bf16 v[114:117], v[166:169], v[198:201], v[114:117]
	v_mfma_f32_16x16x32_bf16 v[102:105], v[158:161], v[206:209], v[102:105]
	v_mfma_f32_16x16x32_bf16 v[98:101], v[166:169], v[206:209], v[98:101]
	v_mfma_f32_16x16x32_bf16 v[86:89], v[158:161], v[214:217], v[86:89]
	v_mfma_f32_16x16x32_bf16 v[78:81], v[166:169], v[214:217], v[78:81]
	s_setprio 0
	s_setprio 1
	v_mfma_f32_16x16x32_bf16 v[110:113], v[170:173], v[186:189], v[110:113]
	v_mfma_f32_16x16x32_bf16 v[106:109], v[178:181], v[186:189], v[106:109]
	v_mfma_f32_16x16x32_bf16 v[94:97], v[170:173], v[194:197], v[94:97]
	v_mfma_f32_16x16x32_bf16 v[90:93], v[178:181], v[194:197], v[90:93]
	v_mfma_f32_16x16x32_bf16 v[82:85], v[170:173], v[202:205], v[82:85]
	v_mfma_f32_16x16x32_bf16 v[74:77], v[178:181], v[202:205], v[74:77]
	v_mfma_f32_16x16x32_bf16 v[70:73], v[170:173], v[210:213], v[70:73]
	v_mfma_f32_16x16x32_bf16 v[66:69], v[178:181], v[210:213], v[66:69]
	s_setprio 3
	s_barrier
	v_mfma_f32_16x16x32_bf16 v[110:113], v[174:177], v[190:193], v[110:113]
	v_mfma_f32_16x16x32_bf16 v[106:109], v[182:185], v[190:193], v[106:109]
	v_mfma_f32_16x16x32_bf16 v[94:97], v[174:177], v[198:201], v[94:97]
	v_mfma_f32_16x16x32_bf16 v[90:93], v[182:185], v[198:201], v[90:93]
	v_mfma_f32_16x16x32_bf16 v[82:85], v[174:177], v[206:209], v[82:85]
	v_mfma_f32_16x16x32_bf16 v[74:77], v[182:185], v[206:209], v[74:77]
	v_mfma_f32_16x16x32_bf16 v[70:73], v[174:177], v[214:217], v[70:73]
	v_mfma_f32_16x16x32_bf16 v[66:69], v[182:185], v[214:217], v[66:69]
	s_setprio 0
	s_add_i32 s69, s61, s53
	v_lshl_add_u64 v[150:151], s[48:49], 0, v[132:133]
	s_mov_b32 m0, s69
	ds_read_b128 v[186:189], v156 offset:16384
	ds_read_b128 v[190:193], v156 offset:17408
	ds_read_b128 v[194:197], v156 offset:18432
	ds_read_b128 v[198:201], v156 offset:19456
	ds_read_b128 v[202:205], v156 offset:20480
	ds_read_b128 v[206:209], v156 offset:21504
	ds_read_b128 v[210:213], v156 offset:22528
	ds_read_b128 v[214:217], v156 offset:23552
	global_load_lds_dwordx4 v[150:151], off
	s_add_i32 m0, s69, 0x2000
	s_add_u32 s70, s48, 0x100000
	v_lshl_add_u64 v[218:219], s[48:49], 0, v[136:137]
	s_addc_u32 s71, s49, 0
	s_add_i32 s69, s62, s53
	global_load_lds_dwordx4 v[218:219], off
	v_lshl_add_u64 v[220:221], s[70:71], 0, v[132:133]
	s_mov_b32 m0, s69
	v_lshl_add_u64 v[222:223], s[50:51], 0, v[134:135]
	global_load_lds_dwordx4 v[220:221], off
	v_lshl_add_u64 v[220:221], s[70:71], 0, v[136:137]
	s_add_i32 m0, s69, 0x2000
	s_nop 0
	global_load_lds_dwordx4 v[220:221], off
	v_lshl_add_u64 v[220:221], s[50:51], 0, v[130:131]
	s_mov_b32 m0, s45
	s_nop 0
	global_load_lds_dwordx4 v[220:221], off
	s_mov_b32 m0, s54
	s_nop 0
	global_load_lds_dwordx4 v[222:223], off
	s_waitcnt vmcnt(8)
	s_waitcnt lgkmcnt(0)
	s_barrier
	s_setprio 1
	s_waitcnt lgkmcnt(0)
	v_mfma_f32_16x16x32_bf16 v[62:65], v[146:149], v[186:189], v[62:65]
	v_mfma_f32_16x16x32_bf16 v[58:61], v[162:165], v[186:189], v[58:61]
	v_mfma_f32_16x16x32_bf16 v[50:53], v[146:149], v[194:197], v[50:53]
	v_mfma_f32_16x16x32_bf16 v[42:45], v[162:165], v[194:197], v[42:45]
	v_mfma_f32_16x16x32_bf16 v[38:41], v[146:149], v[202:205], v[38:41]
	v_mfma_f32_16x16x32_bf16 v[30:33], v[162:165], v[202:205], v[30:33]
	v_mfma_f32_16x16x32_bf16 v[22:25], v[146:149], v[210:213], v[22:25]
	v_mfma_f32_16x16x32_bf16 v[14:17], v[162:165], v[210:213], v[14:17]
	v_mfma_f32_16x16x32_bf16 v[62:65], v[158:161], v[190:193], v[62:65]
	v_mfma_f32_16x16x32_bf16 v[58:61], v[166:169], v[190:193], v[58:61]
	v_mfma_f32_16x16x32_bf16 v[50:53], v[158:161], v[198:201], v[50:53]
	v_mfma_f32_16x16x32_bf16 v[42:45], v[166:169], v[198:201], v[42:45]
	v_mfma_f32_16x16x32_bf16 v[38:41], v[158:161], v[206:209], v[38:41]
	v_mfma_f32_16x16x32_bf16 v[30:33], v[166:169], v[206:209], v[30:33]
	v_mfma_f32_16x16x32_bf16 v[22:25], v[158:161], v[214:217], v[22:25]
	v_mfma_f32_16x16x32_bf16 v[14:17], v[166:169], v[214:217], v[14:17]
	s_setprio 0
	s_setprio 1
	v_mfma_f32_16x16x32_bf16 v[54:57], v[170:173], v[186:189], v[54:57]
	v_mfma_f32_16x16x32_bf16 v[46:49], v[178:181], v[186:189], v[46:49]
	v_mfma_f32_16x16x32_bf16 v[34:37], v[170:173], v[194:197], v[34:37]
	v_mfma_f32_16x16x32_bf16 v[26:29], v[178:181], v[194:197], v[26:29]
	v_mfma_f32_16x16x32_bf16 v[18:21], v[170:173], v[202:205], v[18:21]
	v_mfma_f32_16x16x32_bf16 v[10:13], v[178:181], v[202:205], v[10:13]
	v_mfma_f32_16x16x32_bf16 v[6:9], v[170:173], v[210:213], v[6:9]
	v_mfma_f32_16x16x32_bf16 v[2:5], v[178:181], v[210:213], v[2:5]
	s_setprio 3
	s_barrier
	v_mfma_f32_16x16x32_bf16 v[54:57], v[174:177], v[190:193], v[54:57]
	v_mfma_f32_16x16x32_bf16 v[46:49], v[182:185], v[190:193], v[46:49]
	v_mfma_f32_16x16x32_bf16 v[34:37], v[174:177], v[198:201], v[34:37]
	v_mfma_f32_16x16x32_bf16 v[26:29], v[182:185], v[198:201], v[26:29]
	v_mfma_f32_16x16x32_bf16 v[18:21], v[174:177], v[206:209], v[18:21]
	v_mfma_f32_16x16x32_bf16 v[10:13], v[182:185], v[206:209], v[10:13]
	v_mfma_f32_16x16x32_bf16 v[6:9], v[174:177], v[214:217], v[6:9]
	v_mfma_f32_16x16x32_bf16 v[2:5], v[182:185], v[214:217], v[2:5]
	s_setprio 0
	s_add_i32 s69, 0, 0x18000
	v_add_u32_e32 v157, s69, v152
	s_add_i32 s70, 0, 0x1c000
	ds_read_b128 v[146:149], v157
	ds_read_b128 v[158:161], v157 offset:1024
	ds_read_b128 v[162:165], v157 offset:2048
	ds_read_b128 v[166:169], v157 offset:3072
	v_add_u32_e32 v157, s70, v152
	ds_read_b128 v[170:173], v157
	ds_read_b128 v[174:177], v157 offset:1024
	ds_read_b128 v[178:181], v157 offset:2048
	ds_read_b128 v[182:185], v157 offset:3072
	s_add_u32 s50, s50, 0x100000
	s_addc_u32 s51, s51, 0
	s_mov_b32 m0, s55
	v_lshl_add_u64 v[224:225], s[50:51], 0, v[130:131]
	ds_read_b128 v[186:189], v156 offset:32768
	ds_read_b128 v[190:193], v156 offset:33792
	ds_read_b128 v[194:197], v156 offset:34816
	ds_read_b128 v[198:201], v156 offset:35840
	ds_read_b128 v[202:205], v156 offset:36864
	ds_read_b128 v[206:209], v156 offset:37888
	ds_read_b128 v[210:213], v156 offset:38912
	ds_read_b128 v[214:217], v156 offset:39936
	global_load_lds_dwordx4 v[224:225], off
	v_lshl_add_u64 v[224:225], s[50:51], 0, v[134:135]
	s_mov_b32 m0, s56
	s_nop 0
	global_load_lds_dwordx4 v[224:225], off
	s_waitcnt vmcnt(8)
	s_waitcnt lgkmcnt(0)
	s_barrier
	s_setprio 1
	s_waitcnt lgkmcnt(0)
	v_mfma_f32_16x16x32_bf16 v[126:129], v[146:149], v[186:189], v[126:129]
	v_mfma_f32_16x16x32_bf16 v[122:125], v[162:165], v[186:189], v[122:125]
	v_mfma_f32_16x16x32_bf16 v[118:121], v[146:149], v[194:197], v[118:121]
	v_mfma_f32_16x16x32_bf16 v[114:117], v[162:165], v[194:197], v[114:117]
	v_mfma_f32_16x16x32_bf16 v[102:105], v[146:149], v[202:205], v[102:105]
	v_mfma_f32_16x16x32_bf16 v[98:101], v[162:165], v[202:205], v[98:101]
	v_mfma_f32_16x16x32_bf16 v[86:89], v[146:149], v[210:213], v[86:89]
	v_mfma_f32_16x16x32_bf16 v[78:81], v[162:165], v[210:213], v[78:81]
	v_mfma_f32_16x16x32_bf16 v[126:129], v[158:161], v[190:193], v[126:129]
	v_mfma_f32_16x16x32_bf16 v[122:125], v[166:169], v[190:193], v[122:125]
	v_mfma_f32_16x16x32_bf16 v[118:121], v[158:161], v[198:201], v[118:121]
	v_mfma_f32_16x16x32_bf16 v[114:117], v[166:169], v[198:201], v[114:117]
	v_mfma_f32_16x16x32_bf16 v[102:105], v[158:161], v[206:209], v[102:105]
	v_mfma_f32_16x16x32_bf16 v[98:101], v[166:169], v[206:209], v[98:101]
	v_mfma_f32_16x16x32_bf16 v[86:89], v[158:161], v[214:217], v[86:89]
	v_mfma_f32_16x16x32_bf16 v[78:81], v[166:169], v[214:217], v[78:81]
	s_setprio 0
	s_setprio 1
	v_mfma_f32_16x16x32_bf16 v[110:113], v[170:173], v[186:189], v[110:113]
	v_mfma_f32_16x16x32_bf16 v[106:109], v[178:181], v[186:189], v[106:109]
	v_mfma_f32_16x16x32_bf16 v[94:97], v[170:173], v[194:197], v[94:97]
	v_mfma_f32_16x16x32_bf16 v[90:93], v[178:181], v[194:197], v[90:93]
	v_mfma_f32_16x16x32_bf16 v[82:85], v[170:173], v[202:205], v[82:85]
	v_mfma_f32_16x16x32_bf16 v[74:77], v[178:181], v[202:205], v[74:77]
	v_mfma_f32_16x16x32_bf16 v[70:73], v[170:173], v[210:213], v[70:73]
	v_mfma_f32_16x16x32_bf16 v[66:69], v[178:181], v[210:213], v[66:69]
	s_setprio 3
	s_barrier
	v_mfma_f32_16x16x32_bf16 v[110:113], v[174:177], v[190:193], v[110:113]
	v_mfma_f32_16x16x32_bf16 v[106:109], v[182:185], v[190:193], v[106:109]
	v_mfma_f32_16x16x32_bf16 v[94:97], v[174:177], v[198:201], v[94:97]
	v_mfma_f32_16x16x32_bf16 v[90:93], v[182:185], v[198:201], v[90:93]
	v_mfma_f32_16x16x32_bf16 v[82:85], v[174:177], v[206:209], v[82:85]
	v_mfma_f32_16x16x32_bf16 v[74:77], v[182:185], v[206:209], v[74:77]
	v_mfma_f32_16x16x32_bf16 v[70:73], v[174:177], v[214:217], v[70:73]
	v_mfma_f32_16x16x32_bf16 v[66:69], v[182:185], v[214:217], v[66:69]
	s_setprio 0
	s_add_i32 s50, s69, s53
	v_lshl_add_u64 v[150:151], v[150:151], 0, s[28:29]
	s_mov_b32 m0, s50
	ds_read_b128 v[186:189], v156 offset:49152
	ds_read_b128 v[190:193], v156 offset:50176
	ds_read_b128 v[194:197], v156 offset:51200
	ds_read_b128 v[198:201], v156 offset:52224
	ds_read_b128 v[202:205], v156 offset:53248
	ds_read_b128 v[206:209], v156 offset:54272
	ds_read_b128 v[210:213], v156 offset:55296
	ds_read_b128 v[214:217], v156 offset:56320
	global_load_lds_dwordx4 v[150:151], off
	s_add_i32 m0, s50, 0x2000
	s_add_u32 s48, s48, 0x100080
	v_lshl_add_u64 v[150:151], v[218:219], 0, s[28:29]
	s_addc_u32 s49, s49, 0
	s_add_i32 s50, s70, s53
	global_load_lds_dwordx4 v[150:151], off
	v_lshl_add_u64 v[150:151], s[48:49], 0, v[132:133]
	s_mov_b32 m0, s50
	s_nop 0
	global_load_lds_dwordx4 v[150:151], off
	v_lshl_add_u64 v[150:151], s[48:49], 0, v[136:137]
	s_add_i32 m0, s50, 0x2000
	s_nop 0
	global_load_lds_dwordx4 v[150:151], off
	v_lshl_add_u64 v[150:151], v[220:221], 0, s[28:29]
	s_mov_b32 m0, s58
	s_nop 0
	global_load_lds_dwordx4 v[150:151], off
	v_lshl_add_u64 v[150:151], v[222:223], 0, s[28:29]
	s_mov_b32 m0, s59
	s_nop 0
	global_load_lds_dwordx4 v[150:151], off
	s_waitcnt vmcnt(8)
	s_waitcnt lgkmcnt(0)
	s_barrier
	s_setprio 1
	s_waitcnt lgkmcnt(0)
	v_mfma_f32_16x16x32_bf16 v[62:65], v[146:149], v[186:189], v[62:65]
	v_mfma_f32_16x16x32_bf16 v[58:61], v[162:165], v[186:189], v[58:61]
	v_mfma_f32_16x16x32_bf16 v[50:53], v[146:149], v[194:197], v[50:53]
	v_mfma_f32_16x16x32_bf16 v[42:45], v[162:165], v[194:197], v[42:45]
	v_mfma_f32_16x16x32_bf16 v[38:41], v[146:149], v[202:205], v[38:41]
	v_mfma_f32_16x16x32_bf16 v[30:33], v[162:165], v[202:205], v[30:33]
	v_mfma_f32_16x16x32_bf16 v[22:25], v[146:149], v[210:213], v[22:25]
	v_mfma_f32_16x16x32_bf16 v[14:17], v[162:165], v[210:213], v[14:17]
	v_mfma_f32_16x16x32_bf16 v[62:65], v[158:161], v[190:193], v[62:65]
	v_mfma_f32_16x16x32_bf16 v[58:61], v[166:169], v[190:193], v[58:61]
	v_mfma_f32_16x16x32_bf16 v[50:53], v[158:161], v[198:201], v[50:53]
	v_mfma_f32_16x16x32_bf16 v[42:45], v[166:169], v[198:201], v[42:45]
	v_mfma_f32_16x16x32_bf16 v[38:41], v[158:161], v[206:209], v[38:41]
	v_mfma_f32_16x16x32_bf16 v[30:33], v[166:169], v[206:209], v[30:33]
	v_mfma_f32_16x16x32_bf16 v[22:25], v[158:161], v[214:217], v[22:25]
	v_mfma_f32_16x16x32_bf16 v[14:17], v[166:169], v[214:217], v[14:17]
	s_setprio 0
	s_setprio 1
	v_mfma_f32_16x16x32_bf16 v[54:57], v[170:173], v[186:189], v[54:57]
	v_mfma_f32_16x16x32_bf16 v[46:49], v[178:181], v[186:189], v[46:49]
	v_mfma_f32_16x16x32_bf16 v[34:37], v[170:173], v[194:197], v[34:37]
	v_mfma_f32_16x16x32_bf16 v[26:29], v[178:181], v[194:197], v[26:29]
	v_mfma_f32_16x16x32_bf16 v[18:21], v[170:173], v[202:205], v[18:21]
	v_mfma_f32_16x16x32_bf16 v[10:13], v[178:181], v[202:205], v[10:13]
	v_mfma_f32_16x16x32_bf16 v[6:9], v[170:173], v[210:213], v[6:9]
	v_mfma_f32_16x16x32_bf16 v[2:5], v[178:181], v[210:213], v[2:5]
	s_setprio 3
	s_barrier
	v_mfma_f32_16x16x32_bf16 v[54:57], v[174:177], v[190:193], v[54:57]
	v_mfma_f32_16x16x32_bf16 v[46:49], v[182:185], v[190:193], v[46:49]
	v_mfma_f32_16x16x32_bf16 v[34:37], v[174:177], v[198:201], v[34:37]
	v_mfma_f32_16x16x32_bf16 v[26:29], v[182:185], v[198:201], v[26:29]
	v_mfma_f32_16x16x32_bf16 v[18:21], v[174:177], v[206:209], v[18:21]
	v_mfma_f32_16x16x32_bf16 v[10:13], v[182:185], v[206:209], v[10:13]
	v_mfma_f32_16x16x32_bf16 v[6:9], v[174:177], v[214:217], v[6:9]
	v_mfma_f32_16x16x32_bf16 v[2:5], v[182:185], v[214:217], v[2:5]
	s_setprio 0
	s_add_i32 s68, s68, 2
	s_add_u32 s46, s46, 0x100
	s_addc_u32 s47, s47, 0
	s_add_u32 s66, s66, 0x100
	s_addc_u32 s67, s67, 0
	s_cmp_gt_u32 s68, 61
	s_cbranch_scc0 .LBB0_618
	s_and_b64 vcc, exec, s[30:31]
	s_cbranch_vccz .LBB0_621
	s_barrier

.LBB0_743:
	ds_read_b128 v[130:133], v197
	ds_read_b128 v[134:137], v197 offset:1024
	ds_read_b128 v[138:141], v197 offset:2048
	ds_read_b128 v[142:145], v197 offset:3072
	ds_read_b128 v[146:149], v198
	ds_read_b128 v[150:153], v198 offset:1024
	ds_read_b128 v[154:157], v198 offset:2048
	ds_read_b128 v[158:161], v198 offset:3072
	s_add_u32 s72, s70, 0xfff00080
	s_addc_u32 s73, s71, -1
	s_cmp_eq_u32 s95, 60
	s_cselect_b32 s75, s61, s73
	s_cselect_b32 s74, s67, s72
	s_cselect_b32 s73, s59, s94
	s_cselect_b32 s72, s69, s93
	v_lshl_add_u64 v[184:185], s[70:71], 0, v[176:177]
	s_add_i32 m0, s78, 0xc000
	ds_read_b128 v[200:203], v199
	ds_read_b128 v[204:207], v199 offset:1024
	ds_read_b128 v[208:211], v199 offset:2048
	ds_read_b128 v[212:215], v199 offset:3072
	ds_read_b128 v[216:219], v199 offset:4096
	ds_read_b128 v[220:223], v199 offset:5120
	ds_read_b128 v[224:227], v199 offset:6144
	ds_read_b128 v[228:231], v199 offset:7168
	global_load_lds_dwordx4 v[184:185], off
	v_lshl_add_u64 v[184:185], s[70:71], 0, v[178:179]
	s_add_i32 m0, s78, 0xe000
	s_nop 0
	global_load_lds_dwordx4 v[184:185], off
	s_waitcnt vmcnt(8)
	s_waitcnt lgkmcnt(0)
	s_barrier
	s_setprio 1
	s_waitcnt lgkmcnt(0)
	v_mfma_f32_16x16x32_bf16 v[102:105], v[130:133], v[200:203], v[102:105]
	v_mfma_f32_16x16x32_bf16 v[98:101], v[138:141], v[200:203], v[98:101]
	v_mfma_f32_16x16x32_bf16 v[110:113], v[130:133], v[208:211], v[110:113]
	v_mfma_f32_16x16x32_bf16 v[106:109], v[138:141], v[208:211], v[106:109]
	v_mfma_f32_16x16x32_bf16 v[118:121], v[130:133], v[216:219], v[118:121]
	v_mfma_f32_16x16x32_bf16 v[114:117], v[138:141], v[216:219], v[114:117]
	v_mfma_f32_16x16x32_bf16 v[126:129], v[130:133], v[224:227], v[126:129]
	v_mfma_f32_16x16x32_bf16 v[122:125], v[138:141], v[224:227], v[122:125]
	v_mfma_f32_16x16x32_bf16 v[102:105], v[134:137], v[204:207], v[102:105]
	v_mfma_f32_16x16x32_bf16 v[98:101], v[142:145], v[204:207], v[98:101]
	v_mfma_f32_16x16x32_bf16 v[110:113], v[134:137], v[212:215], v[110:113]
	v_mfma_f32_16x16x32_bf16 v[106:109], v[142:145], v[212:215], v[106:109]
	v_mfma_f32_16x16x32_bf16 v[118:121], v[134:137], v[220:223], v[118:121]
	v_mfma_f32_16x16x32_bf16 v[114:117], v[142:145], v[220:223], v[114:117]
	v_mfma_f32_16x16x32_bf16 v[126:129], v[134:137], v[228:231], v[126:129]
	v_mfma_f32_16x16x32_bf16 v[122:125], v[142:145], v[228:231], v[122:125]
	s_setprio 0
	s_setprio 1
	v_mfma_f32_16x16x32_bf16 v[38:41], v[146:149], v[200:203], v[38:41]
	v_mfma_f32_16x16x32_bf16 v[34:37], v[154:157], v[200:203], v[34:37]
	v_mfma_f32_16x16x32_bf16 v[46:49], v[146:149], v[208:211], v[46:49]
	v_mfma_f32_16x16x32_bf16 v[42:45], v[154:157], v[208:211], v[42:45]
	v_mfma_f32_16x16x32_bf16 v[54:57], v[146:149], v[216:219], v[54:57]
	v_mfma_f32_16x16x32_bf16 v[50:53], v[154:157], v[216:219], v[50:53]
	v_mfma_f32_16x16x32_bf16 v[62:65], v[146:149], v[224:227], v[62:65]
	v_mfma_f32_16x16x32_bf16 v[58:61], v[154:157], v[224:227], v[58:61]
	s_setprio 3
	s_barrier
	v_mfma_f32_16x16x32_bf16 v[38:41], v[150:153], v[204:207], v[38:41]
	v_mfma_f32_16x16x32_bf16 v[34:37], v[158:161], v[204:207], v[34:37]
	v_mfma_f32_16x16x32_bf16 v[46:49], v[150:153], v[212:215], v[46:49]
	v_mfma_f32_16x16x32_bf16 v[42:45], v[158:161], v[212:215], v[42:45]
	v_mfma_f32_16x16x32_bf16 v[54:57], v[150:153], v[220:223], v[54:57]
	v_mfma_f32_16x16x32_bf16 v[50:53], v[158:161], v[220:223], v[50:53]
	v_mfma_f32_16x16x32_bf16 v[62:65], v[150:153], v[228:231], v[62:65]
	v_mfma_f32_16x16x32_bf16 v[58:61], v[158:161], v[228:231], v[58:61]
	s_setprio 0
	s_add_i32 s96, s90, s77
	v_lshl_add_u64 v[184:185], s[72:73], 0, v[164:165]
	s_mov_b32 m0, s96
	ds_read_b128 v[200:203], v199 offset:16384
	ds_read_b128 v[204:207], v199 offset:17408
	ds_read_b128 v[208:211], v199 offset:18432
	ds_read_b128 v[212:215], v199 offset:19456
	ds_read_b128 v[216:219], v199 offset:20480
	ds_read_b128 v[220:223], v199 offset:21504
	ds_read_b128 v[224:227], v199 offset:22528
	ds_read_b128 v[228:231], v199 offset:23552
	global_load_lds_dwordx4 v[184:185], off
	s_add_i32 m0, s96, 0x2000
	s_add_u32 s96, s72, 0x100000
	v_lshl_add_u64 v[232:233], s[72:73], 0, v[168:169]
	s_addc_u32 s97, s73, 0
	s_add_i32 vcc_lo, s91, s77
	global_load_lds_dwordx4 v[232:233], off
	v_lshl_add_u64 v[234:235], s[96:97], 0, v[164:165]
	s_mov_b32 m0, vcc_lo
	v_lshl_add_u64 v[236:237], s[74:75], 0, v[166:167]
	global_load_lds_dwordx4 v[234:235], off
	v_lshl_add_u64 v[234:235], s[96:97], 0, v[168:169]
	s_add_i32 m0, vcc_lo, 0x2000
	s_nop 0
	global_load_lds_dwordx4 v[234:235], off
	v_lshl_add_u64 v[234:235], s[74:75], 0, v[162:163]
	s_mov_b32 m0, s78
	s_nop 0
	global_load_lds_dwordx4 v[234:235], off
	s_mov_b32 m0, s79
	s_nop 0
	global_load_lds_dwordx4 v[236:237], off
	s_waitcnt vmcnt(8)
	s_waitcnt lgkmcnt(0)
	s_barrier
	s_setprio 1
	s_waitcnt lgkmcnt(0)
	v_mfma_f32_16x16x32_bf16 v[70:73], v[130:133], v[200:203], v[70:73]
	v_mfma_f32_16x16x32_bf16 v[66:69], v[138:141], v[200:203], v[66:69]
	v_mfma_f32_16x16x32_bf16 v[78:81], v[130:133], v[208:211], v[78:81]
	v_mfma_f32_16x16x32_bf16 v[74:77], v[138:141], v[208:211], v[74:77]
	v_mfma_f32_16x16x32_bf16 v[86:89], v[130:133], v[216:219], v[86:89]
	v_mfma_f32_16x16x32_bf16 v[82:85], v[138:141], v[216:219], v[82:85]
	v_mfma_f32_16x16x32_bf16 v[94:97], v[130:133], v[224:227], v[94:97]
	v_mfma_f32_16x16x32_bf16 v[90:93], v[138:141], v[224:227], v[90:93]
	v_mfma_f32_16x16x32_bf16 v[70:73], v[134:137], v[204:207], v[70:73]
	v_mfma_f32_16x16x32_bf16 v[66:69], v[142:145], v[204:207], v[66:69]
	v_mfma_f32_16x16x32_bf16 v[78:81], v[134:137], v[212:215], v[78:81]
	v_mfma_f32_16x16x32_bf16 v[74:77], v[142:145], v[212:215], v[74:77]
	v_mfma_f32_16x16x32_bf16 v[86:89], v[134:137], v[220:223], v[86:89]
	v_mfma_f32_16x16x32_bf16 v[82:85], v[142:145], v[220:223], v[82:85]
	v_mfma_f32_16x16x32_bf16 v[94:97], v[134:137], v[228:231], v[94:97]
	v_mfma_f32_16x16x32_bf16 v[90:93], v[142:145], v[228:231], v[90:93]
	s_setprio 0
	s_setprio 1
	v_mfma_f32_16x16x32_bf16 v[6:9], v[146:149], v[200:203], v[6:9]
	v_mfma_f32_16x16x32_bf16 v[2:5], v[154:157], v[200:203], v[2:5]
	v_mfma_f32_16x16x32_bf16 v[14:17], v[146:149], v[208:211], v[14:17]
	v_mfma_f32_16x16x32_bf16 v[10:13], v[154:157], v[208:211], v[10:13]
	v_mfma_f32_16x16x32_bf16 v[22:25], v[146:149], v[216:219], v[22:25]
	v_mfma_f32_16x16x32_bf16 v[18:21], v[154:157], v[216:219], v[18:21]
	v_mfma_f32_16x16x32_bf16 v[30:33], v[146:149], v[224:227], v[30:33]
	v_mfma_f32_16x16x32_bf16 v[26:29], v[154:157], v[224:227], v[26:29]
	s_setprio 3
	s_barrier
	v_mfma_f32_16x16x32_bf16 v[6:9], v[150:153], v[204:207], v[6:9]
	v_mfma_f32_16x16x32_bf16 v[2:5], v[158:161], v[204:207], v[2:5]
	v_mfma_f32_16x16x32_bf16 v[14:17], v[150:153], v[212:215], v[14:17]
	v_mfma_f32_16x16x32_bf16 v[10:13], v[158:161], v[212:215], v[10:13]
	v_mfma_f32_16x16x32_bf16 v[22:25], v[150:153], v[220:223], v[22:25]
	v_mfma_f32_16x16x32_bf16 v[18:21], v[158:161], v[220:223], v[18:21]
	v_mfma_f32_16x16x32_bf16 v[30:33], v[150:153], v[228:231], v[30:33]
	v_mfma_f32_16x16x32_bf16 v[26:29], v[158:161], v[228:231], v[26:29]
	s_setprio 0
	s_add_i32 s96, 0, 0x18000
	s_add_i32 s97, 0, 0x1c000
	v_add_u32_e32 v142, s96, v173
	v_add_u32_e32 v158, s97, v173
	ds_read_b128 v[130:133], v142
	ds_read_b128 v[134:137], v142 offset:1024
	ds_read_b128 v[138:141], v142 offset:2048
	ds_read_b128 v[142:145], v142 offset:3072
	ds_read_b128 v[146:149], v158
	ds_read_b128 v[150:153], v158 offset:1024
	ds_read_b128 v[154:157], v158 offset:2048
	ds_read_b128 v[158:161], v158 offset:3072
	s_add_u32 s74, s74, 0x100000
	s_addc_u32 s75, s75, 0
	s_mov_b32 m0, s80
	v_lshl_add_u64 v[238:239], s[74:75], 0, v[162:163]
	ds_read_b128 v[200:203], v199 offset:32768
	ds_read_b128 v[204:207], v199 offset:33792
	ds_read_b128 v[208:211], v199 offset:34816
	ds_read_b128 v[212:215], v199 offset:35840
	ds_read_b128 v[216:219], v199 offset:36864
	ds_read_b128 v[220:223], v199 offset:37888
	ds_read_b128 v[224:227], v199 offset:38912
	ds_read_b128 v[228:231], v199 offset:39936
	global_load_lds_dwordx4 v[238:239], off
	v_lshl_add_u64 v[238:239], s[74:75], 0, v[166:167]
	s_mov_b32 m0, s81
	s_nop 0
	global_load_lds_dwordx4 v[238:239], off
	s_waitcnt vmcnt(8)
	s_waitcnt lgkmcnt(0)
	s_barrier
	s_setprio 1
	s_waitcnt lgkmcnt(0)
	v_mfma_f32_16x16x32_bf16 v[102:105], v[130:133], v[200:203], v[102:105]
	v_mfma_f32_16x16x32_bf16 v[98:101], v[138:141], v[200:203], v[98:101]
	v_mfma_f32_16x16x32_bf16 v[110:113], v[130:133], v[208:211], v[110:113]
	v_mfma_f32_16x16x32_bf16 v[106:109], v[138:141], v[208:211], v[106:109]
	v_mfma_f32_16x16x32_bf16 v[118:121], v[130:133], v[216:219], v[118:121]
	v_mfma_f32_16x16x32_bf16 v[114:117], v[138:141], v[216:219], v[114:117]
	v_mfma_f32_16x16x32_bf16 v[126:129], v[130:133], v[224:227], v[126:129]
	v_mfma_f32_16x16x32_bf16 v[122:125], v[138:141], v[224:227], v[122:125]
	v_mfma_f32_16x16x32_bf16 v[102:105], v[134:137], v[204:207], v[102:105]
	v_mfma_f32_16x16x32_bf16 v[98:101], v[142:145], v[204:207], v[98:101]
	v_mfma_f32_16x16x32_bf16 v[110:113], v[134:137], v[212:215], v[110:113]
	v_mfma_f32_16x16x32_bf16 v[106:109], v[142:145], v[212:215], v[106:109]
	v_mfma_f32_16x16x32_bf16 v[118:121], v[134:137], v[220:223], v[118:121]
	v_mfma_f32_16x16x32_bf16 v[114:117], v[142:145], v[220:223], v[114:117]
	v_mfma_f32_16x16x32_bf16 v[126:129], v[134:137], v[228:231], v[126:129]
	v_mfma_f32_16x16x32_bf16 v[122:125], v[142:145], v[228:231], v[122:125]
	s_setprio 0
	s_setprio 1
	v_mfma_f32_16x16x32_bf16 v[38:41], v[146:149], v[200:203], v[38:41]
	v_mfma_f32_16x16x32_bf16 v[34:37], v[154:157], v[200:203], v[34:37]
	v_mfma_f32_16x16x32_bf16 v[46:49], v[146:149], v[208:211], v[46:49]
	v_mfma_f32_16x16x32_bf16 v[42:45], v[154:157], v[208:211], v[42:45]
	v_mfma_f32_16x16x32_bf16 v[54:57], v[146:149], v[216:219], v[54:57]
	v_mfma_f32_16x16x32_bf16 v[50:53], v[154:157], v[216:219], v[50:53]
	v_mfma_f32_16x16x32_bf16 v[62:65], v[146:149], v[224:227], v[62:65]
	v_mfma_f32_16x16x32_bf16 v[58:61], v[154:157], v[224:227], v[58:61]
	s_setprio 3
	s_barrier
	v_mfma_f32_16x16x32_bf16 v[38:41], v[150:153], v[204:207], v[38:41]
	v_mfma_f32_16x16x32_bf16 v[34:37], v[158:161], v[204:207], v[34:37]
	v_mfma_f32_16x16x32_bf16 v[46:49], v[150:153], v[212:215], v[46:49]
	v_mfma_f32_16x16x32_bf16 v[42:45], v[158:161], v[212:215], v[42:45]
	v_mfma_f32_16x16x32_bf16 v[54:57], v[150:153], v[220:223], v[54:57]
	v_mfma_f32_16x16x32_bf16 v[50:53], v[158:161], v[220:223], v[50:53]
	v_mfma_f32_16x16x32_bf16 v[62:65], v[150:153], v[228:231], v[62:65]
	v_mfma_f32_16x16x32_bf16 v[58:61], v[158:161], v[228:231], v[58:61]
	s_setprio 0
	s_add_i32 s74, s96, s77
	v_lshl_add_u64 v[184:185], v[184:185], 0, s[38:39]
	s_mov_b32 m0, s74
	ds_read_b128 v[200:203], v199 offset:49152
	ds_read_b128 v[204:207], v199 offset:50176
	ds_read_b128 v[208:211], v199 offset:51200
	ds_read_b128 v[212:215], v199 offset:52224
	ds_read_b128 v[216:219], v199 offset:53248
	ds_read_b128 v[220:223], v199 offset:54272
	ds_read_b128 v[224:227], v199 offset:55296
	ds_read_b128 v[228:231], v199 offset:56320
	global_load_lds_dwordx4 v[184:185], off
	s_add_i32 m0, s74, 0x2000
	s_add_u32 s72, s72, 0x100080
	v_lshl_add_u64 v[184:185], v[232:233], 0, s[38:39]
	s_addc_u32 s73, s73, 0
	s_add_i32 s74, s97, s77
	global_load_lds_dwordx4 v[184:185], off
	v_lshl_add_u64 v[184:185], s[72:73], 0, v[164:165]
	s_mov_b32 m0, s74
	s_nop 0
	global_load_lds_dwordx4 v[184:185], off
	v_lshl_add_u64 v[184:185], s[72:73], 0, v[168:169]
	s_add_i32 m0, s74, 0x2000
	s_nop 0
	global_load_lds_dwordx4 v[184:185], off
	v_lshl_add_u64 v[184:185], v[234:235], 0, s[38:39]
	s_mov_b32 m0, s85
	s_nop 0
	global_load_lds_dwordx4 v[184:185], off
	v_lshl_add_u64 v[184:185], v[236:237], 0, s[38:39]
	s_mov_b32 m0, s86
	s_nop 0
	global_load_lds_dwordx4 v[184:185], off
	s_waitcnt vmcnt(8)
	s_waitcnt lgkmcnt(0)
	s_barrier
	s_setprio 1
	s_waitcnt lgkmcnt(0)
	v_mfma_f32_16x16x32_bf16 v[70:73], v[130:133], v[200:203], v[70:73]
	v_mfma_f32_16x16x32_bf16 v[66:69], v[138:141], v[200:203], v[66:69]
	v_mfma_f32_16x16x32_bf16 v[78:81], v[130:133], v[208:211], v[78:81]
	v_mfma_f32_16x16x32_bf16 v[74:77], v[138:141], v[208:211], v[74:77]
	v_mfma_f32_16x16x32_bf16 v[86:89], v[130:133], v[216:219], v[86:89]
	v_mfma_f32_16x16x32_bf16 v[82:85], v[138:141], v[216:219], v[82:85]
	v_mfma_f32_16x16x32_bf16 v[94:97], v[130:133], v[224:227], v[94:97]
	v_mfma_f32_16x16x32_bf16 v[90:93], v[138:141], v[224:227], v[90:93]
	v_mfma_f32_16x16x32_bf16 v[70:73], v[134:137], v[204:207], v[70:73]
	v_mfma_f32_16x16x32_bf16 v[66:69], v[142:145], v[204:207], v[66:69]
	v_mfma_f32_16x16x32_bf16 v[78:81], v[134:137], v[212:215], v[78:81]
	v_mfma_f32_16x16x32_bf16 v[74:77], v[142:145], v[212:215], v[74:77]
	v_mfma_f32_16x16x32_bf16 v[86:89], v[134:137], v[220:223], v[86:89]
	v_mfma_f32_16x16x32_bf16 v[82:85], v[142:145], v[220:223], v[82:85]
	v_mfma_f32_16x16x32_bf16 v[94:97], v[134:137], v[228:231], v[94:97]
	v_mfma_f32_16x16x32_bf16 v[90:93], v[142:145], v[228:231], v[90:93]
	s_setprio 0
	s_setprio 1
	v_mfma_f32_16x16x32_bf16 v[6:9], v[146:149], v[200:203], v[6:9]
	v_mfma_f32_16x16x32_bf16 v[2:5], v[154:157], v[200:203], v[2:5]
	v_mfma_f32_16x16x32_bf16 v[14:17], v[146:149], v[208:211], v[14:17]
	v_mfma_f32_16x16x32_bf16 v[10:13], v[154:157], v[208:211], v[10:13]
	v_mfma_f32_16x16x32_bf16 v[22:25], v[146:149], v[216:219], v[22:25]
	v_mfma_f32_16x16x32_bf16 v[18:21], v[154:157], v[216:219], v[18:21]
	v_mfma_f32_16x16x32_bf16 v[30:33], v[146:149], v[224:227], v[30:33]
	v_mfma_f32_16x16x32_bf16 v[26:29], v[154:157], v[224:227], v[26:29]
	s_setprio 3
	s_barrier
	v_mfma_f32_16x16x32_bf16 v[6:9], v[150:153], v[204:207], v[6:9]
	v_mfma_f32_16x16x32_bf16 v[2:5], v[158:161], v[204:207], v[2:5]
	v_mfma_f32_16x16x32_bf16 v[14:17], v[150:153], v[212:215], v[14:17]
	v_mfma_f32_16x16x32_bf16 v[10:13], v[158:161], v[212:215], v[10:13]
	v_mfma_f32_16x16x32_bf16 v[22:25], v[150:153], v[220:223], v[22:25]
	v_mfma_f32_16x16x32_bf16 v[18:21], v[158:161], v[220:223], v[18:21]
	v_mfma_f32_16x16x32_bf16 v[30:33], v[150:153], v[228:231], v[30:33]
	v_mfma_f32_16x16x32_bf16 v[26:29], v[158:161], v[228:231], v[26:29]
	s_setprio 0
	s_add_i32 s95, s95, 2
	s_add_u32 s70, s70, 0x100
	s_addc_u32 s71, s71, 0
	s_add_u32 s93, s93, 0x100
	s_addc_u32 s94, s94, 0
	s_cmp_gt_u32 s95, 61
	s_cbranch_scc0 .LBB0_743
	s_and_b64 vcc, exec, s[40:41]
	s_cbranch_vccz .LBB0_746
	s_barrier

.LBB0_902:
	ds_read_b128 v[144:147], v155
	ds_read_b128 v[148:151], v155 offset:1024
	ds_read_b128 v[158:161], v155 offset:2048
	ds_read_b128 v[162:165], v155 offset:3072
	ds_read_b128 v[166:169], v156
	ds_read_b128 v[170:173], v156 offset:1024
	ds_read_b128 v[174:177], v156 offset:2048
	ds_read_b128 v[178:181], v156 offset:3072
	s_add_u32 s50, s48, 0x100
	s_addc_u32 s51, s49, 0
	s_cmpk_eq_i32 s73, 0xa8
	s_cselect_b32 s55, s9, s51
	s_cselect_b32 s54, s8, s50
	s_cselect_b32 s53, s47, s72
	s_cselect_b32 s52, s46, s71
	v_lshl_add_u64 v[214:215], s[48:49], 0, v[136:137]
	s_add_i32 m0, s57, 0xc000
	ds_read_b128 v[182:185], v157
	ds_read_b128 v[186:189], v157 offset:1024
	ds_read_b128 v[190:193], v157 offset:2048
	ds_read_b128 v[194:197], v157 offset:3072
	ds_read_b128 v[198:201], v157 offset:4096
	ds_read_b128 v[202:205], v157 offset:5120
	ds_read_b128 v[206:209], v157 offset:6144
	ds_read_b128 v[210:213], v157 offset:7168
	global_load_lds_dwordx4 v[214:215], off
	v_lshl_add_u64 v[214:215], s[48:49], 0, v[138:139]
	s_add_i32 m0, s57, 0xe000
	s_nop 0
	global_load_lds_dwordx4 v[214:215], off
	s_waitcnt vmcnt(8)
	s_waitcnt lgkmcnt(0)
	s_barrier
	s_setprio 1
	s_waitcnt lgkmcnt(0)
	v_mfma_f32_16x16x32_bf16 v[124:127], v[144:147], v[182:185], v[124:127]
	v_mfma_f32_16x16x32_bf16 v[120:123], v[158:161], v[182:185], v[120:123]
	v_mfma_f32_16x16x32_bf16 v[116:119], v[144:147], v[190:193], v[116:119]
	v_mfma_f32_16x16x32_bf16 v[112:115], v[158:161], v[190:193], v[112:115]
	v_mfma_f32_16x16x32_bf16 v[92:95], v[144:147], v[198:201], v[92:95]
	v_mfma_f32_16x16x32_bf16 v[88:91], v[158:161], v[198:201], v[88:91]
	v_mfma_f32_16x16x32_bf16 v[76:79], v[144:147], v[206:209], v[76:79]
	v_mfma_f32_16x16x32_bf16 v[72:75], v[158:161], v[206:209], v[72:75]
	v_mfma_f32_16x16x32_bf16 v[124:127], v[148:151], v[186:189], v[124:127]
	v_mfma_f32_16x16x32_bf16 v[120:123], v[162:165], v[186:189], v[120:123]
	v_mfma_f32_16x16x32_bf16 v[116:119], v[148:151], v[194:197], v[116:119]
	v_mfma_f32_16x16x32_bf16 v[112:115], v[162:165], v[194:197], v[112:115]
	v_mfma_f32_16x16x32_bf16 v[92:95], v[148:151], v[202:205], v[92:95]
	v_mfma_f32_16x16x32_bf16 v[88:91], v[162:165], v[202:205], v[88:91]
	v_mfma_f32_16x16x32_bf16 v[76:79], v[148:151], v[210:213], v[76:79]
	v_mfma_f32_16x16x32_bf16 v[72:75], v[162:165], v[210:213], v[72:75]
	s_setprio 0
	s_setprio 1
	v_mfma_f32_16x16x32_bf16 v[108:111], v[166:169], v[182:185], v[108:111]
	v_mfma_f32_16x16x32_bf16 v[104:107], v[174:177], v[182:185], v[104:107]
	v_mfma_f32_16x16x32_bf16 v[100:103], v[166:169], v[190:193], v[100:103]
	v_mfma_f32_16x16x32_bf16 v[96:99], v[174:177], v[190:193], v[96:99]
	v_mfma_f32_16x16x32_bf16 v[84:87], v[166:169], v[198:201], v[84:87]
	v_mfma_f32_16x16x32_bf16 v[80:83], v[174:177], v[198:201], v[80:83]
	v_mfma_f32_16x16x32_bf16 v[68:71], v[166:169], v[206:209], v[68:71]
	v_mfma_f32_16x16x32_bf16 v[64:67], v[174:177], v[206:209], v[64:67]
	s_setprio 3
	s_barrier
	v_mfma_f32_16x16x32_bf16 v[108:111], v[170:173], v[186:189], v[108:111]
	v_mfma_f32_16x16x32_bf16 v[104:107], v[178:181], v[186:189], v[104:107]
	v_mfma_f32_16x16x32_bf16 v[100:103], v[170:173], v[194:197], v[100:103]
	v_mfma_f32_16x16x32_bf16 v[96:99], v[178:181], v[194:197], v[96:99]
	v_mfma_f32_16x16x32_bf16 v[84:87], v[170:173], v[202:205], v[84:87]
	v_mfma_f32_16x16x32_bf16 v[80:83], v[178:181], v[202:205], v[80:83]
	v_mfma_f32_16x16x32_bf16 v[68:71], v[170:173], v[210:213], v[68:71]
	v_mfma_f32_16x16x32_bf16 v[64:67], v[178:181], v[210:213], v[64:67]
	s_setprio 0
	s_add_i32 s48, s65, s56
	v_lshl_add_u64 v[214:215], s[52:53], 0, v[130:131]
	s_mov_b32 m0, s48
	ds_read_b128 v[182:185], v157 offset:16384
	ds_read_b128 v[186:189], v157 offset:17408
	ds_read_b128 v[190:193], v157 offset:18432
	ds_read_b128 v[194:197], v157 offset:19456
	ds_read_b128 v[198:201], v157 offset:20480
	ds_read_b128 v[202:205], v157 offset:21504
	ds_read_b128 v[206:209], v157 offset:22528
	ds_read_b128 v[210:213], v157 offset:23552
	global_load_lds_dwordx4 v[214:215], off
	s_add_i32 m0, s48, 0x2000
	s_add_u32 s48, s52, 0x2b0000
	v_lshl_add_u64 v[216:217], s[52:53], 0, v[134:135]
	s_addc_u32 s49, s53, 0
	s_add_i32 s74, s66, s56
	global_load_lds_dwordx4 v[216:217], off
	v_lshl_add_u64 v[218:219], s[48:49], 0, v[130:131]
	s_mov_b32 m0, s74
	v_lshl_add_u64 v[220:221], s[54:55], 0, v[132:133]
	global_load_lds_dwordx4 v[218:219], off
	v_lshl_add_u64 v[218:219], s[48:49], 0, v[134:135]
	s_add_i32 m0, s74, 0x2000
	s_nop 0
	global_load_lds_dwordx4 v[218:219], off
	v_lshl_add_u64 v[218:219], s[54:55], 0, v[128:129]
	s_mov_b32 m0, s57
	s_nop 0
	global_load_lds_dwordx4 v[218:219], off
	s_mov_b32 m0, s58
	s_nop 0
	global_load_lds_dwordx4 v[220:221], off
	s_waitcnt vmcnt(8)
	s_waitcnt lgkmcnt(0)
	s_barrier
	s_setprio 1
	s_waitcnt lgkmcnt(0)
	v_mfma_f32_16x16x32_bf16 v[60:63], v[144:147], v[182:185], v[60:63]
	v_mfma_f32_16x16x32_bf16 v[56:59], v[158:161], v[182:185], v[56:59]
	v_mfma_f32_16x16x32_bf16 v[44:47], v[144:147], v[190:193], v[44:47]
	v_mfma_f32_16x16x32_bf16 v[40:43], v[158:161], v[190:193], v[40:43]
	v_mfma_f32_16x16x32_bf16 v[28:31], v[144:147], v[198:201], v[28:31]
	v_mfma_f32_16x16x32_bf16 v[24:27], v[158:161], v[198:201], v[24:27]
	v_mfma_f32_16x16x32_bf16 v[12:15], v[144:147], v[206:209], v[12:15]
	v_mfma_f32_16x16x32_bf16 v[8:11], v[158:161], v[206:209], v[8:11]
	v_mfma_f32_16x16x32_bf16 v[60:63], v[148:151], v[186:189], v[60:63]
	v_mfma_f32_16x16x32_bf16 v[56:59], v[162:165], v[186:189], v[56:59]
	v_mfma_f32_16x16x32_bf16 v[44:47], v[148:151], v[194:197], v[44:47]
	v_mfma_f32_16x16x32_bf16 v[40:43], v[162:165], v[194:197], v[40:43]
	v_mfma_f32_16x16x32_bf16 v[28:31], v[148:151], v[202:205], v[28:31]
	v_mfma_f32_16x16x32_bf16 v[24:27], v[162:165], v[202:205], v[24:27]
	v_mfma_f32_16x16x32_bf16 v[12:15], v[148:151], v[210:213], v[12:15]
	v_mfma_f32_16x16x32_bf16 v[8:11], v[162:165], v[210:213], v[8:11]
	s_setprio 0
	s_setprio 1
	v_mfma_f32_16x16x32_bf16 v[52:55], v[166:169], v[182:185], v[52:55]
	v_mfma_f32_16x16x32_bf16 v[48:51], v[174:177], v[182:185], v[48:51]
	v_mfma_f32_16x16x32_bf16 v[36:39], v[166:169], v[190:193], v[36:39]
	v_mfma_f32_16x16x32_bf16 v[32:35], v[174:177], v[190:193], v[32:35]
	v_mfma_f32_16x16x32_bf16 v[20:23], v[166:169], v[198:201], v[20:23]
	v_mfma_f32_16x16x32_bf16 v[16:19], v[174:177], v[198:201], v[16:19]
	v_mfma_f32_16x16x32_bf16 v[4:7], v[166:169], v[206:209], v[4:7]
	v_mfma_f32_16x16x32_bf16 v[0:3], v[174:177], v[206:209], v[0:3]
	s_setprio 3
	s_barrier
	v_mfma_f32_16x16x32_bf16 v[52:55], v[170:173], v[186:189], v[52:55]
	v_mfma_f32_16x16x32_bf16 v[48:51], v[178:181], v[186:189], v[48:51]
	v_mfma_f32_16x16x32_bf16 v[36:39], v[170:173], v[194:197], v[36:39]
	v_mfma_f32_16x16x32_bf16 v[32:35], v[178:181], v[194:197], v[32:35]
	v_mfma_f32_16x16x32_bf16 v[20:23], v[170:173], v[202:205], v[20:23]
	v_mfma_f32_16x16x32_bf16 v[16:19], v[178:181], v[202:205], v[16:19]
	v_mfma_f32_16x16x32_bf16 v[4:7], v[170:173], v[210:213], v[4:7]
	v_mfma_f32_16x16x32_bf16 v[0:3], v[178:181], v[210:213], v[0:3]
	s_setprio 0
	s_add_i32 s74, 0, 0x18000
	s_add_i32 s75, 0, 0x1c000
	v_add_u32_e32 v162, s74, v153
	v_add_u32_e32 v178, s75, v153
	ds_read_b128 v[144:147], v162
	ds_read_b128 v[148:151], v162 offset:1024
	ds_read_b128 v[158:161], v162 offset:2048
	ds_read_b128 v[162:165], v162 offset:3072
	ds_read_b128 v[166:169], v178
	ds_read_b128 v[170:173], v178 offset:1024
	ds_read_b128 v[174:177], v178 offset:2048
	ds_read_b128 v[178:181], v178 offset:3072
	s_add_u32 s48, s54, 0x2b0000
	s_addc_u32 s49, s55, 0
	s_mov_b32 m0, s59
	v_lshl_add_u64 v[222:223], s[48:49], 0, v[128:129]
	ds_read_b128 v[182:185], v157 offset:32768
	ds_read_b128 v[186:189], v157 offset:33792
	ds_read_b128 v[190:193], v157 offset:34816
	ds_read_b128 v[194:197], v157 offset:35840
	ds_read_b128 v[198:201], v157 offset:36864
	ds_read_b128 v[202:205], v157 offset:37888
	ds_read_b128 v[206:209], v157 offset:38912
	ds_read_b128 v[210:213], v157 offset:39936
	global_load_lds_dwordx4 v[222:223], off
	v_lshl_add_u64 v[222:223], s[48:49], 0, v[132:133]
	s_mov_b32 m0, s60
	s_nop 0
	global_load_lds_dwordx4 v[222:223], off
	s_waitcnt vmcnt(8)
	s_waitcnt lgkmcnt(0)
	s_barrier
	s_setprio 1
	s_waitcnt lgkmcnt(0)
	v_mfma_f32_16x16x32_bf16 v[124:127], v[144:147], v[182:185], v[124:127]
	v_mfma_f32_16x16x32_bf16 v[120:123], v[158:161], v[182:185], v[120:123]
	v_mfma_f32_16x16x32_bf16 v[116:119], v[144:147], v[190:193], v[116:119]
	v_mfma_f32_16x16x32_bf16 v[112:115], v[158:161], v[190:193], v[112:115]
	v_mfma_f32_16x16x32_bf16 v[92:95], v[144:147], v[198:201], v[92:95]
	v_mfma_f32_16x16x32_bf16 v[88:91], v[158:161], v[198:201], v[88:91]
	v_mfma_f32_16x16x32_bf16 v[76:79], v[144:147], v[206:209], v[76:79]
	v_mfma_f32_16x16x32_bf16 v[72:75], v[158:161], v[206:209], v[72:75]
	v_mfma_f32_16x16x32_bf16 v[124:127], v[148:151], v[186:189], v[124:127]
	v_mfma_f32_16x16x32_bf16 v[120:123], v[162:165], v[186:189], v[120:123]
	v_mfma_f32_16x16x32_bf16 v[116:119], v[148:151], v[194:197], v[116:119]
	v_mfma_f32_16x16x32_bf16 v[112:115], v[162:165], v[194:197], v[112:115]
	v_mfma_f32_16x16x32_bf16 v[92:95], v[148:151], v[202:205], v[92:95]
	v_mfma_f32_16x16x32_bf16 v[88:91], v[162:165], v[202:205], v[88:91]
	v_mfma_f32_16x16x32_bf16 v[76:79], v[148:151], v[210:213], v[76:79]
	v_mfma_f32_16x16x32_bf16 v[72:75], v[162:165], v[210:213], v[72:75]
	s_setprio 0
	s_setprio 1
	v_mfma_f32_16x16x32_bf16 v[108:111], v[166:169], v[182:185], v[108:111]
	v_mfma_f32_16x16x32_bf16 v[104:107], v[174:177], v[182:185], v[104:107]
	v_mfma_f32_16x16x32_bf16 v[100:103], v[166:169], v[190:193], v[100:103]
	v_mfma_f32_16x16x32_bf16 v[96:99], v[174:177], v[190:193], v[96:99]
	v_mfma_f32_16x16x32_bf16 v[84:87], v[166:169], v[198:201], v[84:87]
	v_mfma_f32_16x16x32_bf16 v[80:83], v[174:177], v[198:201], v[80:83]
	v_mfma_f32_16x16x32_bf16 v[68:71], v[166:169], v[206:209], v[68:71]
	v_mfma_f32_16x16x32_bf16 v[64:67], v[174:177], v[206:209], v[64:67]
	s_setprio 3
	s_barrier
	v_mfma_f32_16x16x32_bf16 v[108:111], v[170:173], v[186:189], v[108:111]
	v_mfma_f32_16x16x32_bf16 v[104:107], v[178:181], v[186:189], v[104:107]
	v_mfma_f32_16x16x32_bf16 v[100:103], v[170:173], v[194:197], v[100:103]
	v_mfma_f32_16x16x32_bf16 v[96:99], v[178:181], v[194:197], v[96:99]
	v_mfma_f32_16x16x32_bf16 v[84:87], v[170:173], v[202:205], v[84:87]
	v_mfma_f32_16x16x32_bf16 v[80:83], v[178:181], v[202:205], v[80:83]
	v_mfma_f32_16x16x32_bf16 v[68:71], v[170:173], v[210:213], v[68:71]
	v_mfma_f32_16x16x32_bf16 v[64:67], v[178:181], v[210:213], v[64:67]
	s_setprio 0
	s_add_i32 s48, s74, s56
	v_lshl_add_u64 v[214:215], v[214:215], 0, s[30:31]
	s_mov_b32 m0, s48
	ds_read_b128 v[182:185], v157 offset:49152
	ds_read_b128 v[186:189], v157 offset:50176
	ds_read_b128 v[190:193], v157 offset:51200
	ds_read_b128 v[194:197], v157 offset:52224
	ds_read_b128 v[198:201], v157 offset:53248
	ds_read_b128 v[202:205], v157 offset:54272
	ds_read_b128 v[206:209], v157 offset:55296
	ds_read_b128 v[210:213], v157 offset:56320
	global_load_lds_dwordx4 v[214:215], off
	s_add_i32 m0, s48, 0x2000
	s_add_u32 s48, s52, 0x2b0080
	v_lshl_add_u64 v[214:215], v[216:217], 0, s[30:31]
	s_addc_u32 s49, s53, 0
	s_add_i32 s52, s75, s56
	global_load_lds_dwordx4 v[214:215], off
	v_lshl_add_u64 v[214:215], s[48:49], 0, v[130:131]
	s_mov_b32 m0, s52
	s_nop 0
	global_load_lds_dwordx4 v[214:215], off
	v_lshl_add_u64 v[214:215], s[48:49], 0, v[134:135]
	s_add_i32 m0, s52, 0x2000
	s_nop 0
	global_load_lds_dwordx4 v[214:215], off
	v_lshl_add_u64 v[214:215], v[218:219], 0, s[30:31]
	s_mov_b32 m0, s62
	s_nop 0
	global_load_lds_dwordx4 v[214:215], off
	v_lshl_add_u64 v[214:215], v[220:221], 0, s[30:31]
	s_mov_b32 m0, s63
	s_nop 0
	global_load_lds_dwordx4 v[214:215], off
	s_waitcnt vmcnt(8)
	s_waitcnt lgkmcnt(0)
	s_barrier
	s_setprio 1
	s_waitcnt lgkmcnt(0)
	v_mfma_f32_16x16x32_bf16 v[60:63], v[144:147], v[182:185], v[60:63]
	v_mfma_f32_16x16x32_bf16 v[56:59], v[158:161], v[182:185], v[56:59]
	v_mfma_f32_16x16x32_bf16 v[44:47], v[144:147], v[190:193], v[44:47]
	v_mfma_f32_16x16x32_bf16 v[40:43], v[158:161], v[190:193], v[40:43]
	v_mfma_f32_16x16x32_bf16 v[28:31], v[144:147], v[198:201], v[28:31]
	v_mfma_f32_16x16x32_bf16 v[24:27], v[158:161], v[198:201], v[24:27]
	v_mfma_f32_16x16x32_bf16 v[12:15], v[144:147], v[206:209], v[12:15]
	v_mfma_f32_16x16x32_bf16 v[8:11], v[158:161], v[206:209], v[8:11]
	v_mfma_f32_16x16x32_bf16 v[60:63], v[148:151], v[186:189], v[60:63]
	v_mfma_f32_16x16x32_bf16 v[56:59], v[162:165], v[186:189], v[56:59]
	v_mfma_f32_16x16x32_bf16 v[44:47], v[148:151], v[194:197], v[44:47]
	v_mfma_f32_16x16x32_bf16 v[40:43], v[162:165], v[194:197], v[40:43]
	v_mfma_f32_16x16x32_bf16 v[28:31], v[148:151], v[202:205], v[28:31]
	v_mfma_f32_16x16x32_bf16 v[24:27], v[162:165], v[202:205], v[24:27]
	v_mfma_f32_16x16x32_bf16 v[12:15], v[148:151], v[210:213], v[12:15]
	v_mfma_f32_16x16x32_bf16 v[8:11], v[162:165], v[210:213], v[8:11]
	s_setprio 0
	s_setprio 1
	v_mfma_f32_16x16x32_bf16 v[52:55], v[166:169], v[182:185], v[52:55]
	v_mfma_f32_16x16x32_bf16 v[48:51], v[174:177], v[182:185], v[48:51]
	v_mfma_f32_16x16x32_bf16 v[36:39], v[166:169], v[190:193], v[36:39]
	v_mfma_f32_16x16x32_bf16 v[32:35], v[174:177], v[190:193], v[32:35]
	v_mfma_f32_16x16x32_bf16 v[20:23], v[166:169], v[198:201], v[20:23]
	v_mfma_f32_16x16x32_bf16 v[16:19], v[174:177], v[198:201], v[16:19]
	v_mfma_f32_16x16x32_bf16 v[4:7], v[166:169], v[206:209], v[4:7]
	v_mfma_f32_16x16x32_bf16 v[0:3], v[174:177], v[206:209], v[0:3]
	s_setprio 3
	s_barrier
	v_mfma_f32_16x16x32_bf16 v[52:55], v[170:173], v[186:189], v[52:55]
	v_mfma_f32_16x16x32_bf16 v[48:51], v[178:181], v[186:189], v[48:51]
	v_mfma_f32_16x16x32_bf16 v[36:39], v[170:173], v[194:197], v[36:39]
	v_mfma_f32_16x16x32_bf16 v[32:35], v[178:181], v[194:197], v[32:35]
	v_mfma_f32_16x16x32_bf16 v[20:23], v[170:173], v[202:205], v[20:23]
	v_mfma_f32_16x16x32_bf16 v[16:19], v[178:181], v[202:205], v[16:19]
	v_mfma_f32_16x16x32_bf16 v[4:7], v[170:173], v[210:213], v[4:7]
	v_mfma_f32_16x16x32_bf16 v[0:3], v[178:181], v[210:213], v[0:3]
	s_setprio 0
	s_add_i32 s73, s73, 2
	s_add_u32 s71, s71, 0x100
	s_addc_u32 s72, s72, 0
	s_cmpk_gt_u32 s73, 0xa9
	s_mov_b64 s[48:49], s[50:51]
	s_cbranch_scc0 .LBB0_902
	s_and_b64 vcc, exec, s[34:35]
	s_cbranch_vccz .LBB0_905
	s_barrier
